# unrolled GEMM loops: the k-step byte offset rides in the LDS-DMA instruction offset (compensated in M0), so the tile pointers are never advanced
# speedup vs baseline: 1.0037x; 1.0037x over previous
.LBB0_213:
	s_andn2_b64 vcc, exec, s[6:7]
	s_mov_b64 s[6:7], 0
	s_cbranch_vccnz .LBB0_209
	s_ashr_i32 s39, s38, 31
	s_lshl_b64 s[6:7], s[38:39], 18
	s_add_u32 s72, s3, s6
	s_addc_u32 s73, s33, s7
	s_ashr_i32 s11, s10, 31
	s_lshl_b64 s[34:35], s[10:11], 19
	s_add_u32 s74, s50, s34
	s_addc_u32 s75, s51, s35
	v_readfirstlane_b32 s11, v184
	s_nop 3
	s_lshr_b32 s0, s11, 6
	s_lshr_b32 s39, s11, 4
	s_and_b32 s39, s39, 4
	v_lshl_or_b32 v2, s0, 3, v210
	v_bitop3_b32 v8, s39, v208, v209 bitop3:0x36
	v_lshlrev_b32_e32 v2, 11, v2
	v_lshlrev_b32_e32 v8, 4, v8
	v_or_b32_e32 v144, v2, v8
	v_add_u32_e32 v145, 0x20000, v144
	v_add_u32_e32 v146, 0x40000, v144
	v_add_u32_e32 v147, 0x60000, v144
	s_lshl_b32 s79, s0, 10
	s_lshr_b32 s9, s11, 1
	s_and_b32 s9, s9, 0x1ffffc0
	v_and_or_b32 v4, s11, 64, v189
	v_lshlrev_b32_e32 v106, 7, v4
	v_or_b32_e32 v4, s9, v189
	v_lshlrev_b32_e32 v107, 7, v4
	s_add_u32 s72, s72, 0x780
	s_addc_u32 s73, s73, 0
	s_add_u32 s74, s74, 0x780
	s_addc_u32 s75, s75, 0
	s_add_i32 m0, s79, 0x880
	s_nop 0
	global_load_lds_dwordx4 v144, s[72:73] offset:-1920
	s_add_i32 m0, s79, 0x2880
	s_nop 0
	global_load_lds_dwordx4 v145, s[72:73] offset:-1920
	s_add_i32 m0, s79, 0x4880
	s_nop 0
	global_load_lds_dwordx4 v144, s[74:75] offset:-1920
	s_add_i32 m0, s79, 0x6880
	s_nop 0
	global_load_lds_dwordx4 v145, s[74:75] offset:-1920
	s_add_i32 m0, s79, 0x8880
	s_nop 0
	global_load_lds_dwordx4 v146, s[74:75] offset:-1920
	s_add_i32 m0, s79, 0xa880
	s_nop 0
	global_load_lds_dwordx4 v147, s[74:75] offset:-1920
	s_add_i32 m0, s79, 0xc800
	s_nop 0
	global_load_lds_dwordx4 v144, s[72:73] offset:-1792
	s_add_i32 m0, s79, 0xe800
	s_nop 0
	global_load_lds_dwordx4 v145, s[72:73] offset:-1792
	s_add_i32 m0, s79, 0x10800
	s_nop 0
	global_load_lds_dwordx4 v144, s[74:75] offset:-1792
	s_add_i32 m0, s79, 0x12800
	s_nop 0
	global_load_lds_dwordx4 v145, s[74:75] offset:-1792
	s_add_i32 m0, s79, 0x14800
	s_nop 0
	global_load_lds_dwordx4 v146, s[74:75] offset:-1792
	s_add_i32 m0, s79, 0x16800
	s_nop 0
	global_load_lds_dwordx4 v147, s[74:75] offset:-1792
	s_movk_i32 s81, 0x100
	v_add3_u32 v216, s81, v106, v211
	v_add3_u32 v217, s81, v106, v212
	v_add3_u32 v218, s81, v106, v213
	v_add3_u32 v219, s81, v106, v214
	s_movk_i32 s81, 0x4100
	v_add3_u32 v220, s81, v107, v211
	v_add3_u32 v221, s81, v107, v212
	v_add3_u32 v222, s81, v107, v213
	v_add3_u32 v223, s81, v107, v214
	s_mov_b32 s81, 0x1b800
	v_add_u32_e32 v224, s81, v216
	v_add_u32_e32 v228, s81, v220
	v_add_u32_e32 v225, s81, v217
	v_add_u32_e32 v229, s81, v221
	v_add_u32_e32 v226, s81, v218
	v_add_u32_e32 v230, s81, v222
	v_add_u32_e32 v227, s81, v219
	v_add_u32_e32 v231, s81, v223
	s_waitcnt vmcnt(6)
	s_barrier
	ds_read_b128 v[108:111], v216
	ds_read_b128 v[116:119], v220
	ds_read_b128 v[120:123], v220 offset:4096
	ds_read_b128 v[112:115], v216 offset:4096
.Lg1_loop:
	ds_read_b128 v[126:129], v217
	ds_read_b128 v[134:137], v221
	ds_read_b128 v[138:141], v221 offset:4096
	ds_read_b128 v[130:133], v217 offset:4096
	s_setprio 1
	s_add_i32 m0, s79, 0x1bf80
	s_waitcnt lgkmcnt(6)
	v_mfma_f32_32x32x16_bf16 v[50:65], v[108:111], v[116:119], 0
	global_load_lds_dwordx4 v144, s[72:73] offset:-1664
	s_add_i32 m0, s79, 0x1df80
	s_waitcnt lgkmcnt(5)
	v_mfma_f32_32x32x16_bf16 v[18:33], v[108:111], v[120:123], 0
	global_load_lds_dwordx4 v145, s[72:73] offset:-1664
	s_waitcnt lgkmcnt(4)
	v_mfma_f32_32x32x16_bf16 v[34:49], v[112:115], v[116:119], 0
	v_mfma_f32_32x32x16_bf16 v[2:17], v[112:115], v[120:123], 0
	s_setprio 0
	ds_read_b128 v[108:111], v218
	ds_read_b128 v[116:119], v222
	ds_read_b128 v[120:123], v222 offset:4096
	ds_read_b128 v[112:115], v218 offset:4096
	s_setprio 1
	s_add_i32 m0, s79, 0x1ff80
	s_waitcnt lgkmcnt(6)
	v_mfma_f32_32x32x16_bf16 v[50:65], v[126:129], v[134:137], v[50:65]
	global_load_lds_dwordx4 v144, s[74:75] offset:-1664
	s_add_i32 m0, s79, 0x21f80
	s_waitcnt lgkmcnt(5)
	v_mfma_f32_32x32x16_bf16 v[18:33], v[126:129], v[138:141], v[18:33]
	global_load_lds_dwordx4 v145, s[74:75] offset:-1664
	s_waitcnt lgkmcnt(4)
	v_mfma_f32_32x32x16_bf16 v[34:49], v[130:133], v[134:137], v[34:49]
	v_mfma_f32_32x32x16_bf16 v[2:17], v[130:133], v[138:141], v[2:17]
	s_setprio 0
	ds_read_b128 v[126:129], v219
	ds_read_b128 v[134:137], v223
	ds_read_b128 v[138:141], v223 offset:4096
	ds_read_b128 v[130:133], v219 offset:4096
	s_setprio 1
	s_add_i32 m0, s79, 0x23f80
	s_waitcnt lgkmcnt(6)
	v_mfma_f32_32x32x16_bf16 v[50:65], v[108:111], v[116:119], v[50:65]
	global_load_lds_dwordx4 v146, s[74:75] offset:-1664
	s_add_i32 m0, s79, 0x25f80
	s_waitcnt lgkmcnt(5)
	v_mfma_f32_32x32x16_bf16 v[18:33], v[108:111], v[120:123], v[18:33]
	global_load_lds_dwordx4 v147, s[74:75] offset:-1664
	s_waitcnt lgkmcnt(4)
	v_mfma_f32_32x32x16_bf16 v[34:49], v[112:115], v[116:119], v[34:49]
	v_mfma_f32_32x32x16_bf16 v[2:17], v[112:115], v[120:123], v[2:17]
	s_setprio 0
	s_waitcnt lgkmcnt(0)
	s_waitcnt vmcnt(6)
	s_barrier
	ds_read_b128 v[108:111], v216 offset:49152
	ds_read_b128 v[116:119], v220 offset:49152
	ds_read_b128 v[120:123], v220 offset:53248
	ds_read_b128 v[112:115], v216 offset:53248
	s_setprio 1
	v_mfma_f32_32x32x16_bf16 v[50:65], v[126:129], v[134:137], v[50:65]
	v_mfma_f32_32x32x16_bf16 v[18:33], v[126:129], v[138:141], v[18:33]
	v_mfma_f32_32x32x16_bf16 v[34:49], v[130:133], v[134:137], v[34:49]
	v_mfma_f32_32x32x16_bf16 v[2:17], v[130:133], v[138:141], v[2:17]
	s_setprio 0
	ds_read_b128 v[126:129], v217 offset:49152
	ds_read_b128 v[134:137], v221 offset:49152
	ds_read_b128 v[138:141], v221 offset:53248
	ds_read_b128 v[130:133], v217 offset:53248
	s_setprio 1
	s_add_i32 m0, s79, 0x700
	s_waitcnt lgkmcnt(6)
	v_mfma_f32_32x32x16_bf16 v[50:65], v[108:111], v[116:119], v[50:65]
	global_load_lds_dwordx4 v144, s[72:73] offset:-1536
	s_add_i32 m0, s79, 0x2700
	s_waitcnt lgkmcnt(5)
	v_mfma_f32_32x32x16_bf16 v[18:33], v[108:111], v[120:123], v[18:33]
	global_load_lds_dwordx4 v145, s[72:73] offset:-1536
	s_waitcnt lgkmcnt(4)
	v_mfma_f32_32x32x16_bf16 v[34:49], v[112:115], v[116:119], v[34:49]
	v_mfma_f32_32x32x16_bf16 v[2:17], v[112:115], v[120:123], v[2:17]
	s_setprio 0
	ds_read_b128 v[108:111], v218 offset:49152
	ds_read_b128 v[116:119], v222 offset:49152
	ds_read_b128 v[120:123], v222 offset:53248
	ds_read_b128 v[112:115], v218 offset:53248
	s_setprio 1
	s_add_i32 m0, s79, 0x4700
	s_waitcnt lgkmcnt(6)
	v_mfma_f32_32x32x16_bf16 v[50:65], v[126:129], v[134:137], v[50:65]
	global_load_lds_dwordx4 v144, s[74:75] offset:-1536
	s_add_i32 m0, s79, 0x6700
	s_waitcnt lgkmcnt(5)
	v_mfma_f32_32x32x16_bf16 v[18:33], v[126:129], v[138:141], v[18:33]
	global_load_lds_dwordx4 v145, s[74:75] offset:-1536
	s_waitcnt lgkmcnt(4)
	v_mfma_f32_32x32x16_bf16 v[34:49], v[130:133], v[134:137], v[34:49]
	v_mfma_f32_32x32x16_bf16 v[2:17], v[130:133], v[138:141], v[2:17]
	s_setprio 0
	ds_read_b128 v[126:129], v219 offset:49152
	ds_read_b128 v[134:137], v223 offset:49152
	ds_read_b128 v[138:141], v223 offset:53248
	ds_read_b128 v[130:133], v219 offset:53248
	s_setprio 1
	s_add_i32 m0, s79, 0x8700
	s_waitcnt lgkmcnt(6)
	v_mfma_f32_32x32x16_bf16 v[50:65], v[108:111], v[116:119], v[50:65]
	global_load_lds_dwordx4 v146, s[74:75] offset:-1536
	s_add_i32 m0, s79, 0xa700
	s_waitcnt lgkmcnt(5)
	v_mfma_f32_32x32x16_bf16 v[18:33], v[108:111], v[120:123], v[18:33]
	global_load_lds_dwordx4 v147, s[74:75] offset:-1536
	s_waitcnt lgkmcnt(4)
	v_mfma_f32_32x32x16_bf16 v[34:49], v[112:115], v[116:119], v[34:49]
	v_mfma_f32_32x32x16_bf16 v[2:17], v[112:115], v[120:123], v[2:17]
	s_setprio 0
	s_waitcnt lgkmcnt(0)
	s_waitcnt vmcnt(6)
	s_barrier
	ds_read_b128 v[108:111], v224
	ds_read_b128 v[116:119], v228
	ds_read_b128 v[120:123], v228 offset:4096
	ds_read_b128 v[112:115], v224 offset:4096
	s_setprio 1
	v_mfma_f32_32x32x16_bf16 v[50:65], v[126:129], v[134:137], v[50:65]
	v_mfma_f32_32x32x16_bf16 v[18:33], v[126:129], v[138:141], v[18:33]
	v_mfma_f32_32x32x16_bf16 v[34:49], v[130:133], v[134:137], v[34:49]
	v_mfma_f32_32x32x16_bf16 v[2:17], v[130:133], v[138:141], v[2:17]
	s_setprio 0
	ds_read_b128 v[126:129], v225
	ds_read_b128 v[134:137], v229
	ds_read_b128 v[138:141], v229 offset:4096
	ds_read_b128 v[130:133], v225 offset:4096
	s_setprio 1
	s_add_i32 m0, s79, 0xc680
	s_waitcnt lgkmcnt(6)
	v_mfma_f32_32x32x16_bf16 v[50:65], v[108:111], v[116:119], v[50:65]
	global_load_lds_dwordx4 v144, s[72:73] offset:-1408
	s_add_i32 m0, s79, 0xe680
	s_waitcnt lgkmcnt(5)
	v_mfma_f32_32x32x16_bf16 v[18:33], v[108:111], v[120:123], v[18:33]
	global_load_lds_dwordx4 v145, s[72:73] offset:-1408
	s_waitcnt lgkmcnt(4)
	v_mfma_f32_32x32x16_bf16 v[34:49], v[112:115], v[116:119], v[34:49]
	v_mfma_f32_32x32x16_bf16 v[2:17], v[112:115], v[120:123], v[2:17]
	s_setprio 0
	ds_read_b128 v[108:111], v226
	ds_read_b128 v[116:119], v230
	ds_read_b128 v[120:123], v230 offset:4096
	ds_read_b128 v[112:115], v226 offset:4096
	s_setprio 1
	s_add_i32 m0, s79, 0x10680
	s_waitcnt lgkmcnt(6)
	v_mfma_f32_32x32x16_bf16 v[50:65], v[126:129], v[134:137], v[50:65]
	global_load_lds_dwordx4 v144, s[74:75] offset:-1408
	s_add_i32 m0, s79, 0x12680
	s_waitcnt lgkmcnt(5)
	v_mfma_f32_32x32x16_bf16 v[18:33], v[126:129], v[138:141], v[18:33]
	global_load_lds_dwordx4 v145, s[74:75] offset:-1408
	s_waitcnt lgkmcnt(4)
	v_mfma_f32_32x32x16_bf16 v[34:49], v[130:133], v[134:137], v[34:49]
	v_mfma_f32_32x32x16_bf16 v[2:17], v[130:133], v[138:141], v[2:17]
	s_setprio 0
	ds_read_b128 v[126:129], v227
	ds_read_b128 v[134:137], v231
	ds_read_b128 v[138:141], v231 offset:4096
	ds_read_b128 v[130:133], v227 offset:4096
	s_setprio 1
	s_add_i32 m0, s79, 0x14680
	s_waitcnt lgkmcnt(6)
	v_mfma_f32_32x32x16_bf16 v[50:65], v[108:111], v[116:119], v[50:65]
	global_load_lds_dwordx4 v146, s[74:75] offset:-1408
	s_add_i32 m0, s79, 0x16680
	s_waitcnt lgkmcnt(5)
	v_mfma_f32_32x32x16_bf16 v[18:33], v[108:111], v[120:123], v[18:33]
	global_load_lds_dwordx4 v147, s[74:75] offset:-1408
	s_waitcnt lgkmcnt(4)
	v_mfma_f32_32x32x16_bf16 v[34:49], v[112:115], v[116:119], v[34:49]
	v_mfma_f32_32x32x16_bf16 v[2:17], v[112:115], v[120:123], v[2:17]
	s_setprio 0
	s_waitcnt lgkmcnt(0)
	s_waitcnt vmcnt(6)
	s_barrier
	ds_read_b128 v[108:111], v216
	ds_read_b128 v[116:119], v220
	ds_read_b128 v[120:123], v220 offset:4096
	ds_read_b128 v[112:115], v216 offset:4096
	s_setprio 1
	v_mfma_f32_32x32x16_bf16 v[50:65], v[126:129], v[134:137], v[50:65]
	v_mfma_f32_32x32x16_bf16 v[18:33], v[126:129], v[138:141], v[18:33]
	v_mfma_f32_32x32x16_bf16 v[34:49], v[130:133], v[134:137], v[34:49]
	v_mfma_f32_32x32x16_bf16 v[2:17], v[130:133], v[138:141], v[2:17]
	s_setprio 0
	ds_read_b128 v[126:129], v217
	ds_read_b128 v[134:137], v221
	ds_read_b128 v[138:141], v221 offset:4096
	ds_read_b128 v[130:133], v217 offset:4096
	s_setprio 1
	s_add_i32 m0, s79, 0x1be00
	s_waitcnt lgkmcnt(6)
	v_mfma_f32_32x32x16_bf16 v[50:65], v[108:111], v[116:119], v[50:65]
	global_load_lds_dwordx4 v144, s[72:73] offset:-1280
	s_add_i32 m0, s79, 0x1de00
	s_waitcnt lgkmcnt(5)
	v_mfma_f32_32x32x16_bf16 v[18:33], v[108:111], v[120:123], v[18:33]
	global_load_lds_dwordx4 v145, s[72:73] offset:-1280
	s_waitcnt lgkmcnt(4)
	v_mfma_f32_32x32x16_bf16 v[34:49], v[112:115], v[116:119], v[34:49]
	v_mfma_f32_32x32x16_bf16 v[2:17], v[112:115], v[120:123], v[2:17]
	s_setprio 0
	ds_read_b128 v[108:111], v218
	ds_read_b128 v[116:119], v222
	ds_read_b128 v[120:123], v222 offset:4096
	ds_read_b128 v[112:115], v218 offset:4096
	s_setprio 1
	s_add_i32 m0, s79, 0x1fe00
	s_waitcnt lgkmcnt(6)
	v_mfma_f32_32x32x16_bf16 v[50:65], v[126:129], v[134:137], v[50:65]
	global_load_lds_dwordx4 v144, s[74:75] offset:-1280
	s_add_i32 m0, s79, 0x21e00
	s_waitcnt lgkmcnt(5)
	v_mfma_f32_32x32x16_bf16 v[18:33], v[126:129], v[138:141], v[18:33]
	global_load_lds_dwordx4 v145, s[74:75] offset:-1280
	s_waitcnt lgkmcnt(4)
	v_mfma_f32_32x32x16_bf16 v[34:49], v[130:133], v[134:137], v[34:49]
	v_mfma_f32_32x32x16_bf16 v[2:17], v[130:133], v[138:141], v[2:17]
	s_setprio 0
	ds_read_b128 v[126:129], v219
	ds_read_b128 v[134:137], v223
	ds_read_b128 v[138:141], v223 offset:4096
	ds_read_b128 v[130:133], v219 offset:4096
	s_setprio 1
	s_add_i32 m0, s79, 0x23e00
	s_waitcnt lgkmcnt(6)
	v_mfma_f32_32x32x16_bf16 v[50:65], v[108:111], v[116:119], v[50:65]
	global_load_lds_dwordx4 v146, s[74:75] offset:-1280
	s_add_i32 m0, s79, 0x25e00
	s_waitcnt lgkmcnt(5)
	v_mfma_f32_32x32x16_bf16 v[18:33], v[108:111], v[120:123], v[18:33]
	global_load_lds_dwordx4 v147, s[74:75] offset:-1280
	s_waitcnt lgkmcnt(4)
	v_mfma_f32_32x32x16_bf16 v[34:49], v[112:115], v[116:119], v[34:49]
	v_mfma_f32_32x32x16_bf16 v[2:17], v[112:115], v[120:123], v[2:17]
	s_setprio 0
	s_waitcnt lgkmcnt(0)
	s_waitcnt vmcnt(6)
	s_barrier
	ds_read_b128 v[108:111], v216 offset:49152
	ds_read_b128 v[116:119], v220 offset:49152
	ds_read_b128 v[120:123], v220 offset:53248
	ds_read_b128 v[112:115], v216 offset:53248
	s_setprio 1
	v_mfma_f32_32x32x16_bf16 v[50:65], v[126:129], v[134:137], v[50:65]
	v_mfma_f32_32x32x16_bf16 v[18:33], v[126:129], v[138:141], v[18:33]
	v_mfma_f32_32x32x16_bf16 v[34:49], v[130:133], v[134:137], v[34:49]
	v_mfma_f32_32x32x16_bf16 v[2:17], v[130:133], v[138:141], v[2:17]
	s_setprio 0
	ds_read_b128 v[126:129], v217 offset:49152
	ds_read_b128 v[134:137], v221 offset:49152
	ds_read_b128 v[138:141], v221 offset:53248
	ds_read_b128 v[130:133], v217 offset:53248
	s_setprio 1
	s_add_i32 m0, s79, 0x580
	s_waitcnt lgkmcnt(6)
	v_mfma_f32_32x32x16_bf16 v[50:65], v[108:111], v[116:119], v[50:65]
	global_load_lds_dwordx4 v144, s[72:73] offset:-1152
	s_add_i32 m0, s79, 0x2580
	s_waitcnt lgkmcnt(5)
	v_mfma_f32_32x32x16_bf16 v[18:33], v[108:111], v[120:123], v[18:33]
	global_load_lds_dwordx4 v145, s[72:73] offset:-1152
	s_waitcnt lgkmcnt(4)
	v_mfma_f32_32x32x16_bf16 v[34:49], v[112:115], v[116:119], v[34:49]
	v_mfma_f32_32x32x16_bf16 v[2:17], v[112:115], v[120:123], v[2:17]
	s_setprio 0
	ds_read_b128 v[108:111], v218 offset:49152
	ds_read_b128 v[116:119], v222 offset:49152
	ds_read_b128 v[120:123], v222 offset:53248
	ds_read_b128 v[112:115], v218 offset:53248
	s_setprio 1
	s_add_i32 m0, s79, 0x4580
	s_waitcnt lgkmcnt(6)
	v_mfma_f32_32x32x16_bf16 v[50:65], v[126:129], v[134:137], v[50:65]
	global_load_lds_dwordx4 v144, s[74:75] offset:-1152
	s_add_i32 m0, s79, 0x6580
	s_waitcnt lgkmcnt(5)
	v_mfma_f32_32x32x16_bf16 v[18:33], v[126:129], v[138:141], v[18:33]
	global_load_lds_dwordx4 v145, s[74:75] offset:-1152
	s_waitcnt lgkmcnt(4)
	v_mfma_f32_32x32x16_bf16 v[34:49], v[130:133], v[134:137], v[34:49]
	v_mfma_f32_32x32x16_bf16 v[2:17], v[130:133], v[138:141], v[2:17]
	s_setprio 0
	ds_read_b128 v[126:129], v219 offset:49152
	ds_read_b128 v[134:137], v223 offset:49152
	ds_read_b128 v[138:141], v223 offset:53248
	ds_read_b128 v[130:133], v219 offset:53248
	s_setprio 1
	s_add_i32 m0, s79, 0x8580
	s_waitcnt lgkmcnt(6)
	v_mfma_f32_32x32x16_bf16 v[50:65], v[108:111], v[116:119], v[50:65]
	global_load_lds_dwordx4 v146, s[74:75] offset:-1152
	s_add_i32 m0, s79, 0xa580
	s_waitcnt lgkmcnt(5)
	v_mfma_f32_32x32x16_bf16 v[18:33], v[108:111], v[120:123], v[18:33]
	global_load_lds_dwordx4 v147, s[74:75] offset:-1152
	s_waitcnt lgkmcnt(4)
	v_mfma_f32_32x32x16_bf16 v[34:49], v[112:115], v[116:119], v[34:49]
	v_mfma_f32_32x32x16_bf16 v[2:17], v[112:115], v[120:123], v[2:17]
	s_setprio 0
	s_waitcnt lgkmcnt(0)
	s_waitcnt vmcnt(6)
	s_barrier
	ds_read_b128 v[108:111], v224
	ds_read_b128 v[116:119], v228
	ds_read_b128 v[120:123], v228 offset:4096
	ds_read_b128 v[112:115], v224 offset:4096
	s_setprio 1
	v_mfma_f32_32x32x16_bf16 v[50:65], v[126:129], v[134:137], v[50:65]
	v_mfma_f32_32x32x16_bf16 v[18:33], v[126:129], v[138:141], v[18:33]
	v_mfma_f32_32x32x16_bf16 v[34:49], v[130:133], v[134:137], v[34:49]
	v_mfma_f32_32x32x16_bf16 v[2:17], v[130:133], v[138:141], v[2:17]
	s_setprio 0
	ds_read_b128 v[126:129], v225
	ds_read_b128 v[134:137], v229
	ds_read_b128 v[138:141], v229 offset:4096
	ds_read_b128 v[130:133], v225 offset:4096
	s_setprio 1
	s_add_i32 m0, s79, 0xc500
	s_waitcnt lgkmcnt(6)
	v_mfma_f32_32x32x16_bf16 v[50:65], v[108:111], v[116:119], v[50:65]
	global_load_lds_dwordx4 v144, s[72:73] offset:-1024
	s_add_i32 m0, s79, 0xe500
	s_waitcnt lgkmcnt(5)
	v_mfma_f32_32x32x16_bf16 v[18:33], v[108:111], v[120:123], v[18:33]
	global_load_lds_dwordx4 v145, s[72:73] offset:-1024
	s_waitcnt lgkmcnt(4)
	v_mfma_f32_32x32x16_bf16 v[34:49], v[112:115], v[116:119], v[34:49]
	v_mfma_f32_32x32x16_bf16 v[2:17], v[112:115], v[120:123], v[2:17]
	s_setprio 0
	ds_read_b128 v[108:111], v226
	ds_read_b128 v[116:119], v230
	ds_read_b128 v[120:123], v230 offset:4096
	ds_read_b128 v[112:115], v226 offset:4096
	s_setprio 1
	s_add_i32 m0, s79, 0x10500
	s_waitcnt lgkmcnt(6)
	v_mfma_f32_32x32x16_bf16 v[50:65], v[126:129], v[134:137], v[50:65]
	global_load_lds_dwordx4 v144, s[74:75] offset:-1024
	s_add_i32 m0, s79, 0x12500
	s_waitcnt lgkmcnt(5)
	v_mfma_f32_32x32x16_bf16 v[18:33], v[126:129], v[138:141], v[18:33]
	global_load_lds_dwordx4 v145, s[74:75] offset:-1024
	s_waitcnt lgkmcnt(4)
	v_mfma_f32_32x32x16_bf16 v[34:49], v[130:133], v[134:137], v[34:49]
	v_mfma_f32_32x32x16_bf16 v[2:17], v[130:133], v[138:141], v[2:17]
	s_setprio 0
	ds_read_b128 v[126:129], v227
	ds_read_b128 v[134:137], v231
	ds_read_b128 v[138:141], v231 offset:4096
	ds_read_b128 v[130:133], v227 offset:4096
	s_setprio 1
	s_add_i32 m0, s79, 0x14500
	s_waitcnt lgkmcnt(6)
	v_mfma_f32_32x32x16_bf16 v[50:65], v[108:111], v[116:119], v[50:65]
	global_load_lds_dwordx4 v146, s[74:75] offset:-1024
	s_add_i32 m0, s79, 0x16500
	s_waitcnt lgkmcnt(5)
	v_mfma_f32_32x32x16_bf16 v[18:33], v[108:111], v[120:123], v[18:33]
	global_load_lds_dwordx4 v147, s[74:75] offset:-1024
	s_waitcnt lgkmcnt(4)
	v_mfma_f32_32x32x16_bf16 v[34:49], v[112:115], v[116:119], v[34:49]
	v_mfma_f32_32x32x16_bf16 v[2:17], v[112:115], v[120:123], v[2:17]
	s_setprio 0
	s_waitcnt lgkmcnt(0)
	s_waitcnt vmcnt(6)
	s_barrier
	ds_read_b128 v[108:111], v216
	ds_read_b128 v[116:119], v220
	ds_read_b128 v[120:123], v220 offset:4096
	ds_read_b128 v[112:115], v216 offset:4096
	s_setprio 1
	v_mfma_f32_32x32x16_bf16 v[50:65], v[126:129], v[134:137], v[50:65]
	v_mfma_f32_32x32x16_bf16 v[18:33], v[126:129], v[138:141], v[18:33]
	v_mfma_f32_32x32x16_bf16 v[34:49], v[130:133], v[134:137], v[34:49]
	v_mfma_f32_32x32x16_bf16 v[2:17], v[130:133], v[138:141], v[2:17]
	s_setprio 0
	ds_read_b128 v[126:129], v217
	ds_read_b128 v[134:137], v221
	ds_read_b128 v[138:141], v221 offset:4096
	ds_read_b128 v[130:133], v217 offset:4096
	s_setprio 1
	s_add_i32 m0, s79, 0x1bc80
	s_waitcnt lgkmcnt(6)
	v_mfma_f32_32x32x16_bf16 v[50:65], v[108:111], v[116:119], v[50:65]
	global_load_lds_dwordx4 v144, s[72:73] offset:-896
	s_add_i32 m0, s79, 0x1dc80
	s_waitcnt lgkmcnt(5)
	v_mfma_f32_32x32x16_bf16 v[18:33], v[108:111], v[120:123], v[18:33]
	global_load_lds_dwordx4 v145, s[72:73] offset:-896
	s_waitcnt lgkmcnt(4)
	v_mfma_f32_32x32x16_bf16 v[34:49], v[112:115], v[116:119], v[34:49]
	v_mfma_f32_32x32x16_bf16 v[2:17], v[112:115], v[120:123], v[2:17]
	s_setprio 0
	ds_read_b128 v[108:111], v218
	ds_read_b128 v[116:119], v222
	ds_read_b128 v[120:123], v222 offset:4096
	ds_read_b128 v[112:115], v218 offset:4096
	s_setprio 1
	s_add_i32 m0, s79, 0x1fc80
	s_waitcnt lgkmcnt(6)
	v_mfma_f32_32x32x16_bf16 v[50:65], v[126:129], v[134:137], v[50:65]
	global_load_lds_dwordx4 v144, s[74:75] offset:-896
	s_add_i32 m0, s79, 0x21c80
	s_waitcnt lgkmcnt(5)
	v_mfma_f32_32x32x16_bf16 v[18:33], v[126:129], v[138:141], v[18:33]
	global_load_lds_dwordx4 v145, s[74:75] offset:-896
	s_waitcnt lgkmcnt(4)
	v_mfma_f32_32x32x16_bf16 v[34:49], v[130:133], v[134:137], v[34:49]
	v_mfma_f32_32x32x16_bf16 v[2:17], v[130:133], v[138:141], v[2:17]
	s_setprio 0
	ds_read_b128 v[126:129], v219
	ds_read_b128 v[134:137], v223
	ds_read_b128 v[138:141], v223 offset:4096
	ds_read_b128 v[130:133], v219 offset:4096
	s_setprio 1
	s_add_i32 m0, s79, 0x23c80
	s_waitcnt lgkmcnt(6)
	v_mfma_f32_32x32x16_bf16 v[50:65], v[108:111], v[116:119], v[50:65]
	global_load_lds_dwordx4 v146, s[74:75] offset:-896
	s_add_i32 m0, s79, 0x25c80
	s_waitcnt lgkmcnt(5)
	v_mfma_f32_32x32x16_bf16 v[18:33], v[108:111], v[120:123], v[18:33]
	global_load_lds_dwordx4 v147, s[74:75] offset:-896
	s_waitcnt lgkmcnt(4)
	v_mfma_f32_32x32x16_bf16 v[34:49], v[112:115], v[116:119], v[34:49]
	v_mfma_f32_32x32x16_bf16 v[2:17], v[112:115], v[120:123], v[2:17]
	s_setprio 0
	s_waitcnt lgkmcnt(0)
	s_waitcnt vmcnt(6)
	s_barrier
	ds_read_b128 v[108:111], v216 offset:49152
	ds_read_b128 v[116:119], v220 offset:49152
	ds_read_b128 v[120:123], v220 offset:53248
	ds_read_b128 v[112:115], v216 offset:53248
	s_setprio 1
	v_mfma_f32_32x32x16_bf16 v[50:65], v[126:129], v[134:137], v[50:65]
	v_mfma_f32_32x32x16_bf16 v[18:33], v[126:129], v[138:141], v[18:33]
	v_mfma_f32_32x32x16_bf16 v[34:49], v[130:133], v[134:137], v[34:49]
	v_mfma_f32_32x32x16_bf16 v[2:17], v[130:133], v[138:141], v[2:17]
	s_setprio 0
	ds_read_b128 v[126:129], v217 offset:49152
	ds_read_b128 v[134:137], v221 offset:49152
	ds_read_b128 v[138:141], v221 offset:53248
	ds_read_b128 v[130:133], v217 offset:53248
	s_setprio 1
	s_add_i32 m0, s79, 0x400
	s_waitcnt lgkmcnt(6)
	v_mfma_f32_32x32x16_bf16 v[50:65], v[108:111], v[116:119], v[50:65]
	global_load_lds_dwordx4 v144, s[72:73] offset:-768
	s_add_i32 m0, s79, 0x2400
	s_waitcnt lgkmcnt(5)
	v_mfma_f32_32x32x16_bf16 v[18:33], v[108:111], v[120:123], v[18:33]
	global_load_lds_dwordx4 v145, s[72:73] offset:-768
	s_waitcnt lgkmcnt(4)
	v_mfma_f32_32x32x16_bf16 v[34:49], v[112:115], v[116:119], v[34:49]
	v_mfma_f32_32x32x16_bf16 v[2:17], v[112:115], v[120:123], v[2:17]
	s_setprio 0
	ds_read_b128 v[108:111], v218 offset:49152
	ds_read_b128 v[116:119], v222 offset:49152
	ds_read_b128 v[120:123], v222 offset:53248
	ds_read_b128 v[112:115], v218 offset:53248
	s_setprio 1
	s_add_i32 m0, s79, 0x4400
	s_waitcnt lgkmcnt(6)
	v_mfma_f32_32x32x16_bf16 v[50:65], v[126:129], v[134:137], v[50:65]
	global_load_lds_dwordx4 v144, s[74:75] offset:-768
	s_add_i32 m0, s79, 0x6400
	s_waitcnt lgkmcnt(5)
	v_mfma_f32_32x32x16_bf16 v[18:33], v[126:129], v[138:141], v[18:33]
	global_load_lds_dwordx4 v145, s[74:75] offset:-768
	s_waitcnt lgkmcnt(4)
	v_mfma_f32_32x32x16_bf16 v[34:49], v[130:133], v[134:137], v[34:49]
	v_mfma_f32_32x32x16_bf16 v[2:17], v[130:133], v[138:141], v[2:17]
	s_setprio 0
	ds_read_b128 v[126:129], v219 offset:49152
	ds_read_b128 v[134:137], v223 offset:49152
	ds_read_b128 v[138:141], v223 offset:53248
	ds_read_b128 v[130:133], v219 offset:53248
	s_setprio 1
	s_add_i32 m0, s79, 0x8400
	s_waitcnt lgkmcnt(6)
	v_mfma_f32_32x32x16_bf16 v[50:65], v[108:111], v[116:119], v[50:65]
	global_load_lds_dwordx4 v146, s[74:75] offset:-768
	s_add_i32 m0, s79, 0xa400
	s_waitcnt lgkmcnt(5)
	v_mfma_f32_32x32x16_bf16 v[18:33], v[108:111], v[120:123], v[18:33]
	global_load_lds_dwordx4 v147, s[74:75] offset:-768
	s_waitcnt lgkmcnt(4)
	v_mfma_f32_32x32x16_bf16 v[34:49], v[112:115], v[116:119], v[34:49]
	v_mfma_f32_32x32x16_bf16 v[2:17], v[112:115], v[120:123], v[2:17]
	s_setprio 0
	s_waitcnt lgkmcnt(0)
	s_waitcnt vmcnt(6)
	s_barrier
	ds_read_b128 v[108:111], v224
	ds_read_b128 v[116:119], v228
	ds_read_b128 v[120:123], v228 offset:4096
	ds_read_b128 v[112:115], v224 offset:4096
	s_setprio 1
	v_mfma_f32_32x32x16_bf16 v[50:65], v[126:129], v[134:137], v[50:65]
	v_mfma_f32_32x32x16_bf16 v[18:33], v[126:129], v[138:141], v[18:33]
	v_mfma_f32_32x32x16_bf16 v[34:49], v[130:133], v[134:137], v[34:49]
	v_mfma_f32_32x32x16_bf16 v[2:17], v[130:133], v[138:141], v[2:17]
	s_setprio 0
	ds_read_b128 v[126:129], v225
	ds_read_b128 v[134:137], v229
	ds_read_b128 v[138:141], v229 offset:4096
	ds_read_b128 v[130:133], v225 offset:4096
	s_setprio 1
	s_add_i32 m0, s79, 0xc380
	s_waitcnt lgkmcnt(6)
	v_mfma_f32_32x32x16_bf16 v[50:65], v[108:111], v[116:119], v[50:65]
	global_load_lds_dwordx4 v144, s[72:73] offset:-640
	s_add_i32 m0, s79, 0xe380
	s_waitcnt lgkmcnt(5)
	v_mfma_f32_32x32x16_bf16 v[18:33], v[108:111], v[120:123], v[18:33]
	global_load_lds_dwordx4 v145, s[72:73] offset:-640
	s_waitcnt lgkmcnt(4)
	v_mfma_f32_32x32x16_bf16 v[34:49], v[112:115], v[116:119], v[34:49]
	v_mfma_f32_32x32x16_bf16 v[2:17], v[112:115], v[120:123], v[2:17]
	s_setprio 0
	ds_read_b128 v[108:111], v226
	ds_read_b128 v[116:119], v230
	ds_read_b128 v[120:123], v230 offset:4096
	ds_read_b128 v[112:115], v226 offset:4096
	s_setprio 1
	s_add_i32 m0, s79, 0x10380
	s_waitcnt lgkmcnt(6)
	v_mfma_f32_32x32x16_bf16 v[50:65], v[126:129], v[134:137], v[50:65]
	global_load_lds_dwordx4 v144, s[74:75] offset:-640
	s_add_i32 m0, s79, 0x12380
	s_waitcnt lgkmcnt(5)
	v_mfma_f32_32x32x16_bf16 v[18:33], v[126:129], v[138:141], v[18:33]
	global_load_lds_dwordx4 v145, s[74:75] offset:-640
	s_waitcnt lgkmcnt(4)
	v_mfma_f32_32x32x16_bf16 v[34:49], v[130:133], v[134:137], v[34:49]
	v_mfma_f32_32x32x16_bf16 v[2:17], v[130:133], v[138:141], v[2:17]
	s_setprio 0
	ds_read_b128 v[126:129], v227
	ds_read_b128 v[134:137], v231
	ds_read_b128 v[138:141], v231 offset:4096
	ds_read_b128 v[130:133], v227 offset:4096
	s_setprio 1
	s_add_i32 m0, s79, 0x14380
	s_waitcnt lgkmcnt(6)
	v_mfma_f32_32x32x16_bf16 v[50:65], v[108:111], v[116:119], v[50:65]
	global_load_lds_dwordx4 v146, s[74:75] offset:-640
	s_add_i32 m0, s79, 0x16380
	s_waitcnt lgkmcnt(5)
	v_mfma_f32_32x32x16_bf16 v[18:33], v[108:111], v[120:123], v[18:33]
	global_load_lds_dwordx4 v147, s[74:75] offset:-640
	s_waitcnt lgkmcnt(4)
	v_mfma_f32_32x32x16_bf16 v[34:49], v[112:115], v[116:119], v[34:49]
	v_mfma_f32_32x32x16_bf16 v[2:17], v[112:115], v[120:123], v[2:17]
	s_setprio 0
	s_waitcnt lgkmcnt(0)
	s_waitcnt vmcnt(6)
	s_barrier
	ds_read_b128 v[108:111], v216
	ds_read_b128 v[116:119], v220
	ds_read_b128 v[120:123], v220 offset:4096
	ds_read_b128 v[112:115], v216 offset:4096
	s_setprio 1
	v_mfma_f32_32x32x16_bf16 v[50:65], v[126:129], v[134:137], v[50:65]
	v_mfma_f32_32x32x16_bf16 v[18:33], v[126:129], v[138:141], v[18:33]
	v_mfma_f32_32x32x16_bf16 v[34:49], v[130:133], v[134:137], v[34:49]
	v_mfma_f32_32x32x16_bf16 v[2:17], v[130:133], v[138:141], v[2:17]
	s_setprio 0
	ds_read_b128 v[126:129], v217
	ds_read_b128 v[134:137], v221
	ds_read_b128 v[138:141], v221 offset:4096
	ds_read_b128 v[130:133], v217 offset:4096
	s_setprio 1
	s_add_i32 m0, s79, 0x1bb00
	s_waitcnt lgkmcnt(6)
	v_mfma_f32_32x32x16_bf16 v[50:65], v[108:111], v[116:119], v[50:65]
	global_load_lds_dwordx4 v144, s[72:73] offset:-512
	s_add_i32 m0, s79, 0x1db00
	s_waitcnt lgkmcnt(5)
	v_mfma_f32_32x32x16_bf16 v[18:33], v[108:111], v[120:123], v[18:33]
	global_load_lds_dwordx4 v145, s[72:73] offset:-512
	s_waitcnt lgkmcnt(4)
	v_mfma_f32_32x32x16_bf16 v[34:49], v[112:115], v[116:119], v[34:49]
	v_mfma_f32_32x32x16_bf16 v[2:17], v[112:115], v[120:123], v[2:17]
	s_setprio 0
	ds_read_b128 v[108:111], v218
	ds_read_b128 v[116:119], v222
	ds_read_b128 v[120:123], v222 offset:4096
	ds_read_b128 v[112:115], v218 offset:4096
	s_setprio 1
	s_add_i32 m0, s79, 0x1fb00
	s_waitcnt lgkmcnt(6)
	v_mfma_f32_32x32x16_bf16 v[50:65], v[126:129], v[134:137], v[50:65]
	global_load_lds_dwordx4 v144, s[74:75] offset:-512
	s_add_i32 m0, s79, 0x21b00
	s_waitcnt lgkmcnt(5)
	v_mfma_f32_32x32x16_bf16 v[18:33], v[126:129], v[138:141], v[18:33]
	global_load_lds_dwordx4 v145, s[74:75] offset:-512
	s_waitcnt lgkmcnt(4)
	v_mfma_f32_32x32x16_bf16 v[34:49], v[130:133], v[134:137], v[34:49]
	v_mfma_f32_32x32x16_bf16 v[2:17], v[130:133], v[138:141], v[2:17]
	s_setprio 0
	ds_read_b128 v[126:129], v219
	ds_read_b128 v[134:137], v223
	ds_read_b128 v[138:141], v223 offset:4096
	ds_read_b128 v[130:133], v219 offset:4096
	s_setprio 1
	s_add_i32 m0, s79, 0x23b00
	s_waitcnt lgkmcnt(6)
	v_mfma_f32_32x32x16_bf16 v[50:65], v[108:111], v[116:119], v[50:65]
	global_load_lds_dwordx4 v146, s[74:75] offset:-512
	s_add_i32 m0, s79, 0x25b00
	s_waitcnt lgkmcnt(5)
	v_mfma_f32_32x32x16_bf16 v[18:33], v[108:111], v[120:123], v[18:33]
	global_load_lds_dwordx4 v147, s[74:75] offset:-512
	s_waitcnt lgkmcnt(4)
	v_mfma_f32_32x32x16_bf16 v[34:49], v[112:115], v[116:119], v[34:49]
	v_mfma_f32_32x32x16_bf16 v[2:17], v[112:115], v[120:123], v[2:17]
	s_setprio 0
	s_waitcnt lgkmcnt(0)
	s_waitcnt vmcnt(6)
	s_barrier
	ds_read_b128 v[108:111], v216 offset:49152
	ds_read_b128 v[116:119], v220 offset:49152
	ds_read_b128 v[120:123], v220 offset:53248
	ds_read_b128 v[112:115], v216 offset:53248
	s_setprio 1
	v_mfma_f32_32x32x16_bf16 v[50:65], v[126:129], v[134:137], v[50:65]
	v_mfma_f32_32x32x16_bf16 v[18:33], v[126:129], v[138:141], v[18:33]
	v_mfma_f32_32x32x16_bf16 v[34:49], v[130:133], v[134:137], v[34:49]
	v_mfma_f32_32x32x16_bf16 v[2:17], v[130:133], v[138:141], v[2:17]
	s_setprio 0
	ds_read_b128 v[126:129], v217 offset:49152
	ds_read_b128 v[134:137], v221 offset:49152
	ds_read_b128 v[138:141], v221 offset:53248
	ds_read_b128 v[130:133], v217 offset:53248
	s_setprio 1
	s_add_i32 m0, s79, 0x280
	s_waitcnt lgkmcnt(6)
	v_mfma_f32_32x32x16_bf16 v[50:65], v[108:111], v[116:119], v[50:65]
	global_load_lds_dwordx4 v144, s[72:73] offset:-384
	s_add_i32 m0, s79, 0x2280
	s_waitcnt lgkmcnt(5)
	v_mfma_f32_32x32x16_bf16 v[18:33], v[108:111], v[120:123], v[18:33]
	global_load_lds_dwordx4 v145, s[72:73] offset:-384
	s_waitcnt lgkmcnt(4)
	v_mfma_f32_32x32x16_bf16 v[34:49], v[112:115], v[116:119], v[34:49]
	v_mfma_f32_32x32x16_bf16 v[2:17], v[112:115], v[120:123], v[2:17]
	s_setprio 0
	ds_read_b128 v[108:111], v218 offset:49152
	ds_read_b128 v[116:119], v222 offset:49152
	ds_read_b128 v[120:123], v222 offset:53248
	ds_read_b128 v[112:115], v218 offset:53248
	s_setprio 1
	s_add_i32 m0, s79, 0x4280
	s_waitcnt lgkmcnt(6)
	v_mfma_f32_32x32x16_bf16 v[50:65], v[126:129], v[134:137], v[50:65]
	global_load_lds_dwordx4 v144, s[74:75] offset:-384
	s_add_i32 m0, s79, 0x6280
	s_waitcnt lgkmcnt(5)
	v_mfma_f32_32x32x16_bf16 v[18:33], v[126:129], v[138:141], v[18:33]
	global_load_lds_dwordx4 v145, s[74:75] offset:-384
	s_waitcnt lgkmcnt(4)
	v_mfma_f32_32x32x16_bf16 v[34:49], v[130:133], v[134:137], v[34:49]
	v_mfma_f32_32x32x16_bf16 v[2:17], v[130:133], v[138:141], v[2:17]
	s_setprio 0
	ds_read_b128 v[126:129], v219 offset:49152
	ds_read_b128 v[134:137], v223 offset:49152
	ds_read_b128 v[138:141], v223 offset:53248
	ds_read_b128 v[130:133], v219 offset:53248
	s_setprio 1
	s_add_i32 m0, s79, 0x8280
	s_waitcnt lgkmcnt(6)
	v_mfma_f32_32x32x16_bf16 v[50:65], v[108:111], v[116:119], v[50:65]
	global_load_lds_dwordx4 v146, s[74:75] offset:-384
	s_add_i32 m0, s79, 0xa280
	s_waitcnt lgkmcnt(5)
	v_mfma_f32_32x32x16_bf16 v[18:33], v[108:111], v[120:123], v[18:33]
	global_load_lds_dwordx4 v147, s[74:75] offset:-384
	s_waitcnt lgkmcnt(4)
	v_mfma_f32_32x32x16_bf16 v[34:49], v[112:115], v[116:119], v[34:49]
	v_mfma_f32_32x32x16_bf16 v[2:17], v[112:115], v[120:123], v[2:17]
	s_setprio 0
	s_waitcnt lgkmcnt(0)
	s_waitcnt vmcnt(6)
	s_barrier
	ds_read_b128 v[108:111], v224
	ds_read_b128 v[116:119], v228
	ds_read_b128 v[120:123], v228 offset:4096
	ds_read_b128 v[112:115], v224 offset:4096
	s_setprio 1
	v_mfma_f32_32x32x16_bf16 v[50:65], v[126:129], v[134:137], v[50:65]
	v_mfma_f32_32x32x16_bf16 v[18:33], v[126:129], v[138:141], v[18:33]
	v_mfma_f32_32x32x16_bf16 v[34:49], v[130:133], v[134:137], v[34:49]
	v_mfma_f32_32x32x16_bf16 v[2:17], v[130:133], v[138:141], v[2:17]
	s_setprio 0
	ds_read_b128 v[126:129], v225
	ds_read_b128 v[134:137], v229
	ds_read_b128 v[138:141], v229 offset:4096
	ds_read_b128 v[130:133], v225 offset:4096
	s_setprio 1
	s_add_i32 m0, s79, 0xc200
	s_waitcnt lgkmcnt(6)
	v_mfma_f32_32x32x16_bf16 v[50:65], v[108:111], v[116:119], v[50:65]
	global_load_lds_dwordx4 v144, s[72:73] offset:-256
	s_add_i32 m0, s79, 0xe200
	s_waitcnt lgkmcnt(5)
	v_mfma_f32_32x32x16_bf16 v[18:33], v[108:111], v[120:123], v[18:33]
	global_load_lds_dwordx4 v145, s[72:73] offset:-256
	s_waitcnt lgkmcnt(4)
	v_mfma_f32_32x32x16_bf16 v[34:49], v[112:115], v[116:119], v[34:49]
	v_mfma_f32_32x32x16_bf16 v[2:17], v[112:115], v[120:123], v[2:17]
	s_setprio 0
	ds_read_b128 v[108:111], v226
	ds_read_b128 v[116:119], v230
	ds_read_b128 v[120:123], v230 offset:4096
	ds_read_b128 v[112:115], v226 offset:4096
	s_setprio 1
	s_add_i32 m0, s79, 0x10200
	s_waitcnt lgkmcnt(6)
	v_mfma_f32_32x32x16_bf16 v[50:65], v[126:129], v[134:137], v[50:65]
	global_load_lds_dwordx4 v144, s[74:75] offset:-256
	s_add_i32 m0, s79, 0x12200
	s_waitcnt lgkmcnt(5)
	v_mfma_f32_32x32x16_bf16 v[18:33], v[126:129], v[138:141], v[18:33]
	global_load_lds_dwordx4 v145, s[74:75] offset:-256
	s_waitcnt lgkmcnt(4)
	v_mfma_f32_32x32x16_bf16 v[34:49], v[130:133], v[134:137], v[34:49]
	v_mfma_f32_32x32x16_bf16 v[2:17], v[130:133], v[138:141], v[2:17]
	s_setprio 0
	ds_read_b128 v[126:129], v227
	ds_read_b128 v[134:137], v231
	ds_read_b128 v[138:141], v231 offset:4096
	ds_read_b128 v[130:133], v227 offset:4096
	s_setprio 1
	s_add_i32 m0, s79, 0x14200
	s_waitcnt lgkmcnt(6)
	v_mfma_f32_32x32x16_bf16 v[50:65], v[108:111], v[116:119], v[50:65]
	global_load_lds_dwordx4 v146, s[74:75] offset:-256
	s_add_i32 m0, s79, 0x16200
	s_waitcnt lgkmcnt(5)
	v_mfma_f32_32x32x16_bf16 v[18:33], v[108:111], v[120:123], v[18:33]
	global_load_lds_dwordx4 v147, s[74:75] offset:-256
	s_waitcnt lgkmcnt(4)
	v_mfma_f32_32x32x16_bf16 v[34:49], v[112:115], v[116:119], v[34:49]
	v_mfma_f32_32x32x16_bf16 v[2:17], v[112:115], v[120:123], v[2:17]
	s_setprio 0
	s_waitcnt lgkmcnt(0)
	s_waitcnt vmcnt(6)
	s_barrier
	ds_read_b128 v[108:111], v216
	ds_read_b128 v[116:119], v220
	ds_read_b128 v[120:123], v220 offset:4096
	ds_read_b128 v[112:115], v216 offset:4096
	s_setprio 1
	v_mfma_f32_32x32x16_bf16 v[50:65], v[126:129], v[134:137], v[50:65]
	v_mfma_f32_32x32x16_bf16 v[18:33], v[126:129], v[138:141], v[18:33]
	v_mfma_f32_32x32x16_bf16 v[34:49], v[130:133], v[134:137], v[34:49]
	v_mfma_f32_32x32x16_bf16 v[2:17], v[130:133], v[138:141], v[2:17]
	s_setprio 0
	ds_read_b128 v[126:129], v217
	ds_read_b128 v[134:137], v221
	ds_read_b128 v[138:141], v221 offset:4096
	ds_read_b128 v[130:133], v217 offset:4096
	s_setprio 1
	s_add_i32 m0, s79, 0x1b980
	s_waitcnt lgkmcnt(6)
	v_mfma_f32_32x32x16_bf16 v[50:65], v[108:111], v[116:119], v[50:65]
	global_load_lds_dwordx4 v144, s[72:73] offset:-128
	s_add_i32 m0, s79, 0x1d980
	s_waitcnt lgkmcnt(5)
	v_mfma_f32_32x32x16_bf16 v[18:33], v[108:111], v[120:123], v[18:33]
	global_load_lds_dwordx4 v145, s[72:73] offset:-128
	s_waitcnt lgkmcnt(4)
	v_mfma_f32_32x32x16_bf16 v[34:49], v[112:115], v[116:119], v[34:49]
	v_mfma_f32_32x32x16_bf16 v[2:17], v[112:115], v[120:123], v[2:17]
	s_setprio 0
	ds_read_b128 v[108:111], v218
	ds_read_b128 v[116:119], v222
	ds_read_b128 v[120:123], v222 offset:4096
	ds_read_b128 v[112:115], v218 offset:4096
	s_setprio 1
	s_add_i32 m0, s79, 0x1f980
	s_waitcnt lgkmcnt(6)
	v_mfma_f32_32x32x16_bf16 v[50:65], v[126:129], v[134:137], v[50:65]
	global_load_lds_dwordx4 v144, s[74:75] offset:-128
	s_add_i32 m0, s79, 0x21980
	s_waitcnt lgkmcnt(5)
	v_mfma_f32_32x32x16_bf16 v[18:33], v[126:129], v[138:141], v[18:33]
	global_load_lds_dwordx4 v145, s[74:75] offset:-128
	s_waitcnt lgkmcnt(4)
	v_mfma_f32_32x32x16_bf16 v[34:49], v[130:133], v[134:137], v[34:49]
	v_mfma_f32_32x32x16_bf16 v[2:17], v[130:133], v[138:141], v[2:17]
	s_setprio 0
	ds_read_b128 v[126:129], v219
	ds_read_b128 v[134:137], v223
	ds_read_b128 v[138:141], v223 offset:4096
	ds_read_b128 v[130:133], v219 offset:4096
	s_setprio 1
	s_add_i32 m0, s79, 0x23980
	s_waitcnt lgkmcnt(6)
	v_mfma_f32_32x32x16_bf16 v[50:65], v[108:111], v[116:119], v[50:65]
	global_load_lds_dwordx4 v146, s[74:75] offset:-128
	s_add_i32 m0, s79, 0x25980
	s_waitcnt lgkmcnt(5)
	v_mfma_f32_32x32x16_bf16 v[18:33], v[108:111], v[120:123], v[18:33]
	global_load_lds_dwordx4 v147, s[74:75] offset:-128
	s_waitcnt lgkmcnt(4)
	v_mfma_f32_32x32x16_bf16 v[34:49], v[112:115], v[116:119], v[34:49]
	v_mfma_f32_32x32x16_bf16 v[2:17], v[112:115], v[120:123], v[2:17]
	s_setprio 0
	s_waitcnt lgkmcnt(0)
	s_waitcnt vmcnt(6)
	s_barrier
	ds_read_b128 v[108:111], v216 offset:49152
	ds_read_b128 v[116:119], v220 offset:49152
	ds_read_b128 v[120:123], v220 offset:53248
	ds_read_b128 v[112:115], v216 offset:53248
	s_setprio 1
	v_mfma_f32_32x32x16_bf16 v[50:65], v[126:129], v[134:137], v[50:65]
	v_mfma_f32_32x32x16_bf16 v[18:33], v[126:129], v[138:141], v[18:33]
	v_mfma_f32_32x32x16_bf16 v[34:49], v[130:133], v[134:137], v[34:49]
	v_mfma_f32_32x32x16_bf16 v[2:17], v[130:133], v[138:141], v[2:17]
	s_setprio 0
	ds_read_b128 v[126:129], v217 offset:49152
	ds_read_b128 v[134:137], v221 offset:49152
	ds_read_b128 v[138:141], v221 offset:53248
	ds_read_b128 v[130:133], v217 offset:53248
	s_setprio 1
	s_add_i32 m0, s79, 0x100
	s_waitcnt lgkmcnt(6)
	v_mfma_f32_32x32x16_bf16 v[50:65], v[108:111], v[116:119], v[50:65]
	global_load_lds_dwordx4 v144, s[72:73]
	s_add_i32 m0, s79, 0x2100
	s_waitcnt lgkmcnt(5)
	v_mfma_f32_32x32x16_bf16 v[18:33], v[108:111], v[120:123], v[18:33]
	global_load_lds_dwordx4 v145, s[72:73]
	s_waitcnt lgkmcnt(4)
	v_mfma_f32_32x32x16_bf16 v[34:49], v[112:115], v[116:119], v[34:49]
	v_mfma_f32_32x32x16_bf16 v[2:17], v[112:115], v[120:123], v[2:17]
	s_setprio 0
	ds_read_b128 v[108:111], v218 offset:49152
	ds_read_b128 v[116:119], v222 offset:49152
	ds_read_b128 v[120:123], v222 offset:53248
	ds_read_b128 v[112:115], v218 offset:53248
	s_setprio 1
	s_add_i32 m0, s79, 0x4100
	s_waitcnt lgkmcnt(6)
	v_mfma_f32_32x32x16_bf16 v[50:65], v[126:129], v[134:137], v[50:65]
	global_load_lds_dwordx4 v144, s[74:75]
	s_add_i32 m0, s79, 0x6100
	s_waitcnt lgkmcnt(5)
	v_mfma_f32_32x32x16_bf16 v[18:33], v[126:129], v[138:141], v[18:33]
	global_load_lds_dwordx4 v145, s[74:75]
	s_waitcnt lgkmcnt(4)
	v_mfma_f32_32x32x16_bf16 v[34:49], v[130:133], v[134:137], v[34:49]
	v_mfma_f32_32x32x16_bf16 v[2:17], v[130:133], v[138:141], v[2:17]
	s_setprio 0
	ds_read_b128 v[126:129], v219 offset:49152
	ds_read_b128 v[134:137], v223 offset:49152
	ds_read_b128 v[138:141], v223 offset:53248
	ds_read_b128 v[130:133], v219 offset:53248
	s_setprio 1
	s_add_i32 m0, s79, 0x8100
	s_waitcnt lgkmcnt(6)
	v_mfma_f32_32x32x16_bf16 v[50:65], v[108:111], v[116:119], v[50:65]
	global_load_lds_dwordx4 v146, s[74:75]
	s_add_i32 m0, s79, 0xa100
	s_waitcnt lgkmcnt(5)
	v_mfma_f32_32x32x16_bf16 v[18:33], v[108:111], v[120:123], v[18:33]
	global_load_lds_dwordx4 v147, s[74:75]
	s_waitcnt lgkmcnt(4)
	v_mfma_f32_32x32x16_bf16 v[34:49], v[112:115], v[116:119], v[34:49]
	v_mfma_f32_32x32x16_bf16 v[2:17], v[112:115], v[120:123], v[2:17]
	s_setprio 0
	s_waitcnt lgkmcnt(0)
	s_waitcnt vmcnt(6)
	s_barrier
	ds_read_b128 v[108:111], v224
	ds_read_b128 v[116:119], v228
	ds_read_b128 v[120:123], v228 offset:4096
	ds_read_b128 v[112:115], v224 offset:4096
	s_setprio 1
	v_mfma_f32_32x32x16_bf16 v[50:65], v[126:129], v[134:137], v[50:65]
	v_mfma_f32_32x32x16_bf16 v[18:33], v[126:129], v[138:141], v[18:33]
	v_mfma_f32_32x32x16_bf16 v[34:49], v[130:133], v[134:137], v[34:49]
	v_mfma_f32_32x32x16_bf16 v[2:17], v[130:133], v[138:141], v[2:17]
	s_setprio 0
	ds_read_b128 v[126:129], v225
	ds_read_b128 v[134:137], v229
	ds_read_b128 v[138:141], v229 offset:4096
	ds_read_b128 v[130:133], v225 offset:4096
	s_setprio 1
	s_waitcnt lgkmcnt(6)
	v_mfma_f32_32x32x16_bf16 v[50:65], v[108:111], v[116:119], v[50:65]
	s_waitcnt lgkmcnt(5)
	v_mfma_f32_32x32x16_bf16 v[18:33], v[108:111], v[120:123], v[18:33]
	s_waitcnt lgkmcnt(4)
	v_mfma_f32_32x32x16_bf16 v[34:49], v[112:115], v[116:119], v[34:49]
	v_mfma_f32_32x32x16_bf16 v[2:17], v[112:115], v[120:123], v[2:17]
	s_setprio 0
	ds_read_b128 v[108:111], v226
	ds_read_b128 v[116:119], v230
	ds_read_b128 v[120:123], v230 offset:4096
	ds_read_b128 v[112:115], v226 offset:4096
	s_setprio 1
	s_waitcnt lgkmcnt(6)
	v_mfma_f32_32x32x16_bf16 v[50:65], v[126:129], v[134:137], v[50:65]
	s_waitcnt lgkmcnt(5)
	v_mfma_f32_32x32x16_bf16 v[18:33], v[126:129], v[138:141], v[18:33]
	s_waitcnt lgkmcnt(4)
	v_mfma_f32_32x32x16_bf16 v[34:49], v[130:133], v[134:137], v[34:49]
	v_mfma_f32_32x32x16_bf16 v[2:17], v[130:133], v[138:141], v[2:17]
	s_setprio 0
	ds_read_b128 v[126:129], v227
	ds_read_b128 v[134:137], v231
	ds_read_b128 v[138:141], v231 offset:4096
	ds_read_b128 v[130:133], v227 offset:4096
	s_setprio 1
	s_waitcnt lgkmcnt(6)
	v_mfma_f32_32x32x16_bf16 v[50:65], v[108:111], v[116:119], v[50:65]
	s_waitcnt lgkmcnt(5)
	v_mfma_f32_32x32x16_bf16 v[18:33], v[108:111], v[120:123], v[18:33]
	s_waitcnt lgkmcnt(4)
	v_mfma_f32_32x32x16_bf16 v[34:49], v[112:115], v[116:119], v[34:49]
	v_mfma_f32_32x32x16_bf16 v[2:17], v[112:115], v[120:123], v[2:17]
	s_setprio 0
	s_waitcnt lgkmcnt(0)
	s_waitcnt vmcnt(0)
	s_barrier
	ds_read_b128 v[108:111], v216
	ds_read_b128 v[116:119], v220
	ds_read_b128 v[120:123], v220 offset:4096
	ds_read_b128 v[112:115], v216 offset:4096
	s_setprio 1
	v_mfma_f32_32x32x16_bf16 v[50:65], v[126:129], v[134:137], v[50:65]
	v_mfma_f32_32x32x16_bf16 v[18:33], v[126:129], v[138:141], v[18:33]
	v_mfma_f32_32x32x16_bf16 v[34:49], v[130:133], v[134:137], v[34:49]
	v_mfma_f32_32x32x16_bf16 v[2:17], v[130:133], v[138:141], v[2:17]
	s_setprio 0
	ds_read_b128 v[126:129], v217
	ds_read_b128 v[134:137], v221
	ds_read_b128 v[138:141], v221 offset:4096
	ds_read_b128 v[130:133], v217 offset:4096
	s_setprio 1
	s_waitcnt lgkmcnt(6)
	v_mfma_f32_32x32x16_bf16 v[50:65], v[108:111], v[116:119], v[50:65]
	s_waitcnt lgkmcnt(5)
	v_mfma_f32_32x32x16_bf16 v[18:33], v[108:111], v[120:123], v[18:33]
	s_waitcnt lgkmcnt(4)
	v_mfma_f32_32x32x16_bf16 v[34:49], v[112:115], v[116:119], v[34:49]
	v_mfma_f32_32x32x16_bf16 v[2:17], v[112:115], v[120:123], v[2:17]
	s_setprio 0
	ds_read_b128 v[108:111], v218
	ds_read_b128 v[116:119], v222
	ds_read_b128 v[120:123], v222 offset:4096
	ds_read_b128 v[112:115], v218 offset:4096
	s_setprio 1
	s_waitcnt lgkmcnt(6)
	v_mfma_f32_32x32x16_bf16 v[50:65], v[126:129], v[134:137], v[50:65]
	s_waitcnt lgkmcnt(5)
	v_mfma_f32_32x32x16_bf16 v[18:33], v[126:129], v[138:141], v[18:33]
	s_waitcnt lgkmcnt(4)
	v_mfma_f32_32x32x16_bf16 v[34:49], v[130:133], v[134:137], v[34:49]
	v_mfma_f32_32x32x16_bf16 v[2:17], v[130:133], v[138:141], v[2:17]
	s_setprio 0
	ds_read_b128 v[126:129], v219
	ds_read_b128 v[134:137], v223
	ds_read_b128 v[138:141], v223 offset:4096
	ds_read_b128 v[130:133], v219 offset:4096
	s_setprio 1
	s_waitcnt lgkmcnt(6)
	v_mfma_f32_32x32x16_bf16 v[50:65], v[108:111], v[116:119], v[50:65]
	s_waitcnt lgkmcnt(5)
	v_mfma_f32_32x32x16_bf16 v[18:33], v[108:111], v[120:123], v[18:33]
	s_waitcnt lgkmcnt(4)
	v_mfma_f32_32x32x16_bf16 v[34:49], v[112:115], v[116:119], v[34:49]
	v_mfma_f32_32x32x16_bf16 v[2:17], v[112:115], v[120:123], v[2:17]
	s_setprio 0
	s_waitcnt lgkmcnt(0)
	s_waitcnt vmcnt(0)
	s_barrier

.Lg2_ptr:
	s_load_dwordx2 s[30:31], s[34:35], 0x0
	v_readfirstlane_b32 s34, v184
	s_nop 3
	s_lshr_b32 s6, s34, 4
	s_and_b32 s6, s6, 4
	v_bitop3_b32 v6, s6, v208, v209 bitop3:0x36
	v_lshl_or_b32 v2, s49, 3, v210
	v_lshlrev_b32_e32 v2, 11, v2
	v_lshlrev_b32_e32 v6, 4, v6
	v_or_b32_e32 v124, v2, v6
	v_add_u32_e32 v125, 0x20000, v124
	v_add_u32_e32 v126, 0x40000, v124
	v_add_u32_e32 v127, 0x60000, v124
	s_lshl_b32 s19, s49, 10
	s_and_b32 s6, s34, 64
	v_or_b32_e32 v2, s6, v189
	v_lshlrev_b32_e32 v118, 7, v2
	s_lshr_b32 s6, s34, 1
	s_and_b32 s50, s6, 0x7fffffc0
	v_or_b32_e32 v2, s50, v189
	v_lshlrev_b32_e32 v119, 7, v2
	s_mulk_i32 s49, 0x3000
	s_add_i32 s34, s49, 0x100
	v_add3_u32 v240, s34, v72, v74
	v_add3_u32 v83, s34, v187, v73
	s_add_i32 s4, s50, s48
	v_add_u32_e32 v216, s4, v75
	v_add_u32_e32 v217, s4, v76
	v_add_u32_e32 v218, s4, v77
	v_add_u32_e32 v219, s4, v78
	v_add_u32_e32 v220, s4, v79
	v_add_u32_e32 v221, s4, v80
	v_add_u32_e32 v222, s4, v81
	v_add_u32_e32 v223, s4, v82
	v_lshlrev_b32_e32 v216, 2, v216
	v_lshlrev_b32_e32 v217, 2, v217
	v_lshlrev_b32_e32 v218, 2, v218
	v_lshlrev_b32_e32 v219, 2, v219
	v_lshlrev_b32_e32 v220, 2, v220
	v_lshlrev_b32_e32 v221, 2, v221
	v_lshlrev_b32_e32 v222, 2, v222
	v_lshlrev_b32_e32 v223, 2, v223
	v_lshlrev_b32_e32 v68, 2, v188
	s_lshl_b64 s[28:29], s[28:29], 2
	s_add_u32 s6, s54, s28
	s_addc_u32 s7, s55, s29
	s_lshl_b64 s[28:29], s[4:5], 2
	s_add_u32 s28, s6, s28
	s_addc_u32 s29, s7, s29
	v_lshl_add_u64 v[64:65], s[28:29], 0, v[68:69]
	v_add_co_u32_e32 v64, vcc, s46, v64
	s_nop 1
	v_addc_co_u32_e32 v65, vcc, 0, v65, vcc
	s_waitcnt lgkmcnt(0)
	s_add_u32 s26, s30, s26
	s_addc_u32 s27, s31, s27
	s_add_u32 s8, s26, 0x20000
	s_addc_u32 s9, s27, 0
	s_add_u32 s10, s24, 0x20000
	s_addc_u32 s11, s25, 0
	s_add_u32 s12, s12, 0x780
	s_addc_u32 s13, s13, 0
	s_add_u32 s14, s14, 0x780
	s_addc_u32 s15, s15, 0
	s_add_i32 m0, s19, 0x880
	s_nop 0
	global_load_lds_dwordx4 v124, s[12:13] offset:-1920
	s_add_i32 m0, s19, 0x2880
	s_nop 0
	global_load_lds_dwordx4 v125, s[12:13] offset:-1920
	s_add_i32 m0, s19, 0x4880
	s_nop 0
	global_load_lds_dwordx4 v124, s[14:15] offset:-1920
	s_add_i32 m0, s19, 0x6880
	s_nop 0
	global_load_lds_dwordx4 v125, s[14:15] offset:-1920
	s_add_i32 m0, s19, 0x8880
	s_nop 0
	global_load_lds_dwordx4 v126, s[14:15] offset:-1920
	s_add_i32 m0, s19, 0xa880
	s_nop 0
	global_load_lds_dwordx4 v127, s[14:15] offset:-1920
	s_add_i32 m0, s19, 0xc800
	s_nop 0
	global_load_lds_dwordx4 v124, s[12:13] offset:-1792
	s_add_i32 m0, s19, 0xe800
	s_nop 0
	global_load_lds_dwordx4 v125, s[12:13] offset:-1792
	s_add_i32 m0, s19, 0x10800
	s_nop 0
	global_load_lds_dwordx4 v124, s[14:15] offset:-1792
	s_add_i32 m0, s19, 0x12800
	s_nop 0
	global_load_lds_dwordx4 v125, s[14:15] offset:-1792
	s_add_i32 m0, s19, 0x14800
	s_nop 0
	global_load_lds_dwordx4 v126, s[14:15] offset:-1792
	s_add_i32 m0, s19, 0x16800
	s_nop 0
	global_load_lds_dwordx4 v127, s[14:15] offset:-1792
	global_load_dwordx4 v[64:67], v[64:65], off
	global_load_dwordx4 v[128:131], v216, s[26:27]
	global_load_dwordx4 v[132:135], v217, s[26:27]
	global_load_dwordx4 v[136:139], v218, s[26:27]
	global_load_dwordx4 v[140:143], v219, s[26:27]
	global_load_dwordx4 v[144:147], v220, s[26:27]
	global_load_dwordx4 v[148:151], v221, s[26:27]
	global_load_dwordx4 v[152:155], v222, s[26:27]
	global_load_dwordx4 v[156:159], v223, s[26:27]
	global_load_dwordx4 v[160:163], v216, s[8:9]
	global_load_dwordx4 v[164:167], v217, s[8:9]
	global_load_dwordx4 v[168:171], v218, s[8:9]
	global_load_dwordx4 v[172:175], v219, s[8:9]
	global_load_dwordx4 v[176:179], v220, s[8:9]
	global_load_dwordx4 v[180:183], v221, s[8:9]
	global_load_dwordx4 v[190:193], v222, s[8:9]
	global_load_dwordx4 v[194:197], v223, s[8:9]
	s_movk_i32 s21, 0x100
	v_add3_u32 v224, s21, v118, v211
	v_add3_u32 v225, s21, v118, v212
	v_add3_u32 v226, s21, v118, v213
	v_add3_u32 v227, s21, v118, v214
	s_movk_i32 s21, 0x4100
	v_add3_u32 v228, s21, v119, v211
	v_add3_u32 v229, s21, v119, v212
	v_add3_u32 v230, s21, v119, v213
	v_add3_u32 v231, s21, v119, v214
	s_mov_b32 s21, 0x1b800
	v_add_u32_e32 v232, s21, v224
	v_add_u32_e32 v236, s21, v228
	v_add_u32_e32 v233, s21, v225
	v_add_u32_e32 v237, s21, v229
	v_add_u32_e32 v234, s21, v226
	v_add_u32_e32 v238, s21, v230
	v_add_u32_e32 v235, s21, v227
	v_add_u32_e32 v239, s21, v231
	s_waitcnt vmcnt(23)
	s_barrier
	ds_read_b128 v[84:87], v224
	ds_read_b128 v[92:95], v228
	ds_read_b128 v[96:99], v228 offset:4096
	ds_read_b128 v[88:91], v224 offset:4096
.Lg2_loop:
	ds_read_b128 v[102:105], v225
	ds_read_b128 v[110:113], v229
	ds_read_b128 v[114:117], v229 offset:4096
	ds_read_b128 v[106:109], v225 offset:4096
	s_setprio 1
	s_add_i32 m0, s19, 0x1bf80
	s_waitcnt lgkmcnt(6)
	v_mfma_f32_32x32x16_bf16 v[48:63], v[84:87], v[92:95], 0
	global_load_lds_dwordx4 v124, s[12:13] offset:-1664
	s_add_i32 m0, s19, 0x1df80
	s_waitcnt lgkmcnt(5)
	v_mfma_f32_32x32x16_bf16 v[32:47], v[84:87], v[96:99], 0
	global_load_lds_dwordx4 v125, s[12:13] offset:-1664
	s_waitcnt lgkmcnt(4)
	v_mfma_f32_32x32x16_bf16 v[16:31], v[88:91], v[92:95], 0
	v_mfma_f32_32x32x16_bf16 v[0:15], v[88:91], v[96:99], 0
	s_setprio 0
	ds_read_b128 v[84:87], v226
	ds_read_b128 v[92:95], v230
	ds_read_b128 v[96:99], v230 offset:4096
	ds_read_b128 v[88:91], v226 offset:4096
	s_setprio 1
	s_add_i32 m0, s19, 0x1ff80
	s_waitcnt lgkmcnt(6)
	v_mfma_f32_32x32x16_bf16 v[48:63], v[102:105], v[110:113], v[48:63]
	global_load_lds_dwordx4 v124, s[14:15] offset:-1664
	s_add_i32 m0, s19, 0x21f80
	s_waitcnt lgkmcnt(5)
	v_mfma_f32_32x32x16_bf16 v[32:47], v[102:105], v[114:117], v[32:47]
	global_load_lds_dwordx4 v125, s[14:15] offset:-1664
	s_waitcnt lgkmcnt(4)
	v_mfma_f32_32x32x16_bf16 v[16:31], v[106:109], v[110:113], v[16:31]
	v_mfma_f32_32x32x16_bf16 v[0:15], v[106:109], v[114:117], v[0:15]
	s_setprio 0
	ds_read_b128 v[102:105], v227
	ds_read_b128 v[110:113], v231
	ds_read_b128 v[114:117], v231 offset:4096
	ds_read_b128 v[106:109], v227 offset:4096
	s_setprio 1
	s_add_i32 m0, s19, 0x23f80
	s_waitcnt lgkmcnt(6)
	v_mfma_f32_32x32x16_bf16 v[48:63], v[84:87], v[92:95], v[48:63]
	global_load_lds_dwordx4 v126, s[14:15] offset:-1664
	s_add_i32 m0, s19, 0x25f80
	s_waitcnt lgkmcnt(5)
	v_mfma_f32_32x32x16_bf16 v[32:47], v[84:87], v[96:99], v[32:47]
	global_load_lds_dwordx4 v127, s[14:15] offset:-1664
	s_waitcnt lgkmcnt(4)
	v_mfma_f32_32x32x16_bf16 v[16:31], v[88:91], v[92:95], v[16:31]
	v_mfma_f32_32x32x16_bf16 v[0:15], v[88:91], v[96:99], v[0:15]
	s_setprio 0
	s_waitcnt lgkmcnt(0)
	s_waitcnt vmcnt(23)
	s_barrier
	ds_read_b128 v[84:87], v224 offset:49152
	ds_read_b128 v[92:95], v228 offset:49152
	ds_read_b128 v[96:99], v228 offset:53248
	ds_read_b128 v[88:91], v224 offset:53248
	s_setprio 1
	v_mfma_f32_32x32x16_bf16 v[48:63], v[102:105], v[110:113], v[48:63]
	v_mfma_f32_32x32x16_bf16 v[32:47], v[102:105], v[114:117], v[32:47]
	v_mfma_f32_32x32x16_bf16 v[16:31], v[106:109], v[110:113], v[16:31]
	v_mfma_f32_32x32x16_bf16 v[0:15], v[106:109], v[114:117], v[0:15]
	s_setprio 0
	ds_read_b128 v[102:105], v225 offset:49152
	ds_read_b128 v[110:113], v229 offset:49152
	ds_read_b128 v[114:117], v229 offset:53248
	ds_read_b128 v[106:109], v225 offset:53248
	s_setprio 1
	s_add_i32 m0, s19, 0x700
	s_waitcnt lgkmcnt(6)
	v_mfma_f32_32x32x16_bf16 v[48:63], v[84:87], v[92:95], v[48:63]
	global_load_lds_dwordx4 v124, s[12:13] offset:-1536
	s_add_i32 m0, s19, 0x2700
	s_waitcnt lgkmcnt(5)
	v_mfma_f32_32x32x16_bf16 v[32:47], v[84:87], v[96:99], v[32:47]
	global_load_lds_dwordx4 v125, s[12:13] offset:-1536
	s_waitcnt lgkmcnt(4)
	v_mfma_f32_32x32x16_bf16 v[16:31], v[88:91], v[92:95], v[16:31]
	v_mfma_f32_32x32x16_bf16 v[0:15], v[88:91], v[96:99], v[0:15]
	s_setprio 0
	ds_read_b128 v[84:87], v226 offset:49152
	ds_read_b128 v[92:95], v230 offset:49152
	ds_read_b128 v[96:99], v230 offset:53248
	ds_read_b128 v[88:91], v226 offset:53248
	s_setprio 1
	s_add_i32 m0, s19, 0x4700
	s_waitcnt lgkmcnt(6)
	v_mfma_f32_32x32x16_bf16 v[48:63], v[102:105], v[110:113], v[48:63]
	global_load_lds_dwordx4 v124, s[14:15] offset:-1536
	s_add_i32 m0, s19, 0x6700
	s_waitcnt lgkmcnt(5)
	v_mfma_f32_32x32x16_bf16 v[32:47], v[102:105], v[114:117], v[32:47]
	global_load_lds_dwordx4 v125, s[14:15] offset:-1536
	s_waitcnt lgkmcnt(4)
	v_mfma_f32_32x32x16_bf16 v[16:31], v[106:109], v[110:113], v[16:31]
	v_mfma_f32_32x32x16_bf16 v[0:15], v[106:109], v[114:117], v[0:15]
	s_setprio 0
	ds_read_b128 v[102:105], v227 offset:49152
	ds_read_b128 v[110:113], v231 offset:49152
	ds_read_b128 v[114:117], v231 offset:53248
	ds_read_b128 v[106:109], v227 offset:53248
	s_setprio 1
	s_add_i32 m0, s19, 0x8700
	s_waitcnt lgkmcnt(6)
	v_mfma_f32_32x32x16_bf16 v[48:63], v[84:87], v[92:95], v[48:63]
	global_load_lds_dwordx4 v126, s[14:15] offset:-1536
	s_add_i32 m0, s19, 0xa700
	s_waitcnt lgkmcnt(5)
	v_mfma_f32_32x32x16_bf16 v[32:47], v[84:87], v[96:99], v[32:47]
	global_load_lds_dwordx4 v127, s[14:15] offset:-1536
	s_waitcnt lgkmcnt(4)
	v_mfma_f32_32x32x16_bf16 v[16:31], v[88:91], v[92:95], v[16:31]
	v_mfma_f32_32x32x16_bf16 v[0:15], v[88:91], v[96:99], v[0:15]
	s_setprio 0
	s_waitcnt lgkmcnt(0)
	s_waitcnt vmcnt(6)
	s_barrier
	ds_read_b128 v[84:87], v232
	ds_read_b128 v[92:95], v236
	ds_read_b128 v[96:99], v236 offset:4096
	ds_read_b128 v[88:91], v232 offset:4096
	s_setprio 1
	v_mfma_f32_32x32x16_bf16 v[48:63], v[102:105], v[110:113], v[48:63]
	v_mfma_f32_32x32x16_bf16 v[32:47], v[102:105], v[114:117], v[32:47]
	v_mfma_f32_32x32x16_bf16 v[16:31], v[106:109], v[110:113], v[16:31]
	v_mfma_f32_32x32x16_bf16 v[0:15], v[106:109], v[114:117], v[0:15]
	s_setprio 0
	ds_read_b128 v[102:105], v233
	ds_read_b128 v[110:113], v237
	ds_read_b128 v[114:117], v237 offset:4096
	ds_read_b128 v[106:109], v233 offset:4096
	s_setprio 1
	s_add_i32 m0, s19, 0xc680
	s_waitcnt lgkmcnt(6)
	v_mfma_f32_32x32x16_bf16 v[48:63], v[84:87], v[92:95], v[48:63]
	global_load_lds_dwordx4 v124, s[12:13] offset:-1408
	s_add_i32 m0, s19, 0xe680
	s_waitcnt lgkmcnt(5)
	v_mfma_f32_32x32x16_bf16 v[32:47], v[84:87], v[96:99], v[32:47]
	global_load_lds_dwordx4 v125, s[12:13] offset:-1408
	s_waitcnt lgkmcnt(4)
	v_mfma_f32_32x32x16_bf16 v[16:31], v[88:91], v[92:95], v[16:31]
	v_mfma_f32_32x32x16_bf16 v[0:15], v[88:91], v[96:99], v[0:15]
	s_setprio 0
	ds_read_b128 v[84:87], v234
	ds_read_b128 v[92:95], v238
	ds_read_b128 v[96:99], v238 offset:4096
	ds_read_b128 v[88:91], v234 offset:4096
	s_setprio 1
	s_add_i32 m0, s19, 0x10680
	s_waitcnt lgkmcnt(6)
	v_mfma_f32_32x32x16_bf16 v[48:63], v[102:105], v[110:113], v[48:63]
	global_load_lds_dwordx4 v124, s[14:15] offset:-1408
	s_add_i32 m0, s19, 0x12680
	s_waitcnt lgkmcnt(5)
	v_mfma_f32_32x32x16_bf16 v[32:47], v[102:105], v[114:117], v[32:47]
	global_load_lds_dwordx4 v125, s[14:15] offset:-1408
	s_waitcnt lgkmcnt(4)
	v_mfma_f32_32x32x16_bf16 v[16:31], v[106:109], v[110:113], v[16:31]
	v_mfma_f32_32x32x16_bf16 v[0:15], v[106:109], v[114:117], v[0:15]
	s_setprio 0
	ds_read_b128 v[102:105], v235
	ds_read_b128 v[110:113], v239
	ds_read_b128 v[114:117], v239 offset:4096
	ds_read_b128 v[106:109], v235 offset:4096
	s_setprio 1
	s_add_i32 m0, s19, 0x14680
	s_waitcnt lgkmcnt(6)
	v_mfma_f32_32x32x16_bf16 v[48:63], v[84:87], v[92:95], v[48:63]
	global_load_lds_dwordx4 v126, s[14:15] offset:-1408
	s_add_i32 m0, s19, 0x16680
	s_waitcnt lgkmcnt(5)
	v_mfma_f32_32x32x16_bf16 v[32:47], v[84:87], v[96:99], v[32:47]
	global_load_lds_dwordx4 v127, s[14:15] offset:-1408
	s_waitcnt lgkmcnt(4)
	v_mfma_f32_32x32x16_bf16 v[16:31], v[88:91], v[92:95], v[16:31]
	v_mfma_f32_32x32x16_bf16 v[0:15], v[88:91], v[96:99], v[0:15]
	s_setprio 0
	s_waitcnt lgkmcnt(0)
	s_waitcnt vmcnt(6)
	s_barrier
	ds_read_b128 v[84:87], v224
	ds_read_b128 v[92:95], v228
	ds_read_b128 v[96:99], v228 offset:4096
	ds_read_b128 v[88:91], v224 offset:4096
	s_setprio 1
	v_mfma_f32_32x32x16_bf16 v[48:63], v[102:105], v[110:113], v[48:63]
	v_mfma_f32_32x32x16_bf16 v[32:47], v[102:105], v[114:117], v[32:47]
	v_mfma_f32_32x32x16_bf16 v[16:31], v[106:109], v[110:113], v[16:31]
	v_mfma_f32_32x32x16_bf16 v[0:15], v[106:109], v[114:117], v[0:15]
	s_setprio 0
	ds_read_b128 v[102:105], v225
	ds_read_b128 v[110:113], v229
	ds_read_b128 v[114:117], v229 offset:4096
	ds_read_b128 v[106:109], v225 offset:4096
	s_setprio 1
	s_add_i32 m0, s19, 0x1be00
	s_waitcnt lgkmcnt(6)
	v_mfma_f32_32x32x16_bf16 v[48:63], v[84:87], v[92:95], v[48:63]
	global_load_lds_dwordx4 v124, s[12:13] offset:-1280
	s_add_i32 m0, s19, 0x1de00
	s_waitcnt lgkmcnt(5)
	v_mfma_f32_32x32x16_bf16 v[32:47], v[84:87], v[96:99], v[32:47]
	global_load_lds_dwordx4 v125, s[12:13] offset:-1280
	s_waitcnt lgkmcnt(4)
	v_mfma_f32_32x32x16_bf16 v[16:31], v[88:91], v[92:95], v[16:31]
	v_mfma_f32_32x32x16_bf16 v[0:15], v[88:91], v[96:99], v[0:15]
	s_setprio 0
	ds_read_b128 v[84:87], v226
	ds_read_b128 v[92:95], v230
	ds_read_b128 v[96:99], v230 offset:4096
	ds_read_b128 v[88:91], v226 offset:4096
	s_setprio 1
	s_add_i32 m0, s19, 0x1fe00
	s_waitcnt lgkmcnt(6)
	v_mfma_f32_32x32x16_bf16 v[48:63], v[102:105], v[110:113], v[48:63]
	global_load_lds_dwordx4 v124, s[14:15] offset:-1280
	s_add_i32 m0, s19, 0x21e00
	s_waitcnt lgkmcnt(5)
	v_mfma_f32_32x32x16_bf16 v[32:47], v[102:105], v[114:117], v[32:47]
	global_load_lds_dwordx4 v125, s[14:15] offset:-1280
	s_waitcnt lgkmcnt(4)
	v_mfma_f32_32x32x16_bf16 v[16:31], v[106:109], v[110:113], v[16:31]
	v_mfma_f32_32x32x16_bf16 v[0:15], v[106:109], v[114:117], v[0:15]
	s_setprio 0
	ds_read_b128 v[102:105], v227
	ds_read_b128 v[110:113], v231
	ds_read_b128 v[114:117], v231 offset:4096
	ds_read_b128 v[106:109], v227 offset:4096
	s_setprio 1
	s_add_i32 m0, s19, 0x23e00
	s_waitcnt lgkmcnt(6)
	v_mfma_f32_32x32x16_bf16 v[48:63], v[84:87], v[92:95], v[48:63]
	global_load_lds_dwordx4 v126, s[14:15] offset:-1280
	s_add_i32 m0, s19, 0x25e00
	s_waitcnt lgkmcnt(5)
	v_mfma_f32_32x32x16_bf16 v[32:47], v[84:87], v[96:99], v[32:47]
	global_load_lds_dwordx4 v127, s[14:15] offset:-1280
	s_waitcnt lgkmcnt(4)
	v_mfma_f32_32x32x16_bf16 v[16:31], v[88:91], v[92:95], v[16:31]
	v_mfma_f32_32x32x16_bf16 v[0:15], v[88:91], v[96:99], v[0:15]
	s_setprio 0
	s_waitcnt lgkmcnt(0)
	s_waitcnt vmcnt(6)
	s_barrier
	ds_read_b128 v[84:87], v224 offset:49152
	ds_read_b128 v[92:95], v228 offset:49152
	ds_read_b128 v[96:99], v228 offset:53248
	ds_read_b128 v[88:91], v224 offset:53248
	s_setprio 1
	v_mfma_f32_32x32x16_bf16 v[48:63], v[102:105], v[110:113], v[48:63]
	v_mfma_f32_32x32x16_bf16 v[32:47], v[102:105], v[114:117], v[32:47]
	v_mfma_f32_32x32x16_bf16 v[16:31], v[106:109], v[110:113], v[16:31]
	v_mfma_f32_32x32x16_bf16 v[0:15], v[106:109], v[114:117], v[0:15]
	s_setprio 0
	ds_read_b128 v[102:105], v225 offset:49152
	ds_read_b128 v[110:113], v229 offset:49152
	ds_read_b128 v[114:117], v229 offset:53248
	ds_read_b128 v[106:109], v225 offset:53248
	s_setprio 1
	s_add_i32 m0, s19, 0x580
	s_waitcnt lgkmcnt(6)
	v_mfma_f32_32x32x16_bf16 v[48:63], v[84:87], v[92:95], v[48:63]
	global_load_lds_dwordx4 v124, s[12:13] offset:-1152
	s_add_i32 m0, s19, 0x2580
	s_waitcnt lgkmcnt(5)
	v_mfma_f32_32x32x16_bf16 v[32:47], v[84:87], v[96:99], v[32:47]
	global_load_lds_dwordx4 v125, s[12:13] offset:-1152
	s_waitcnt lgkmcnt(4)
	v_mfma_f32_32x32x16_bf16 v[16:31], v[88:91], v[92:95], v[16:31]
	v_mfma_f32_32x32x16_bf16 v[0:15], v[88:91], v[96:99], v[0:15]
	s_setprio 0
	ds_read_b128 v[84:87], v226 offset:49152
	ds_read_b128 v[92:95], v230 offset:49152
	ds_read_b128 v[96:99], v230 offset:53248
	ds_read_b128 v[88:91], v226 offset:53248
	s_setprio 1
	s_add_i32 m0, s19, 0x4580
	s_waitcnt lgkmcnt(6)
	v_mfma_f32_32x32x16_bf16 v[48:63], v[102:105], v[110:113], v[48:63]
	global_load_lds_dwordx4 v124, s[14:15] offset:-1152
	s_add_i32 m0, s19, 0x6580
	s_waitcnt lgkmcnt(5)
	v_mfma_f32_32x32x16_bf16 v[32:47], v[102:105], v[114:117], v[32:47]
	global_load_lds_dwordx4 v125, s[14:15] offset:-1152
	s_waitcnt lgkmcnt(4)
	v_mfma_f32_32x32x16_bf16 v[16:31], v[106:109], v[110:113], v[16:31]
	v_mfma_f32_32x32x16_bf16 v[0:15], v[106:109], v[114:117], v[0:15]
	s_setprio 0
	ds_read_b128 v[102:105], v227 offset:49152
	ds_read_b128 v[110:113], v231 offset:49152
	ds_read_b128 v[114:117], v231 offset:53248
	ds_read_b128 v[106:109], v227 offset:53248
	s_setprio 1
	s_add_i32 m0, s19, 0x8580
	s_waitcnt lgkmcnt(6)
	v_mfma_f32_32x32x16_bf16 v[48:63], v[84:87], v[92:95], v[48:63]
	global_load_lds_dwordx4 v126, s[14:15] offset:-1152
	s_add_i32 m0, s19, 0xa580
	s_waitcnt lgkmcnt(5)
	v_mfma_f32_32x32x16_bf16 v[32:47], v[84:87], v[96:99], v[32:47]
	global_load_lds_dwordx4 v127, s[14:15] offset:-1152
	s_waitcnt lgkmcnt(4)
	v_mfma_f32_32x32x16_bf16 v[16:31], v[88:91], v[92:95], v[16:31]
	v_mfma_f32_32x32x16_bf16 v[0:15], v[88:91], v[96:99], v[0:15]
	s_setprio 0
	s_waitcnt lgkmcnt(0)
	s_waitcnt vmcnt(6)
	s_barrier
	ds_read_b128 v[84:87], v232
	ds_read_b128 v[92:95], v236
	ds_read_b128 v[96:99], v236 offset:4096
	ds_read_b128 v[88:91], v232 offset:4096
	s_setprio 1
	v_mfma_f32_32x32x16_bf16 v[48:63], v[102:105], v[110:113], v[48:63]
	v_mfma_f32_32x32x16_bf16 v[32:47], v[102:105], v[114:117], v[32:47]
	v_mfma_f32_32x32x16_bf16 v[16:31], v[106:109], v[110:113], v[16:31]
	v_mfma_f32_32x32x16_bf16 v[0:15], v[106:109], v[114:117], v[0:15]
	s_setprio 0
	ds_read_b128 v[102:105], v233
	ds_read_b128 v[110:113], v237
	ds_read_b128 v[114:117], v237 offset:4096
	ds_read_b128 v[106:109], v233 offset:4096
	s_setprio 1
	s_add_i32 m0, s19, 0xc500
	s_waitcnt lgkmcnt(6)
	v_mfma_f32_32x32x16_bf16 v[48:63], v[84:87], v[92:95], v[48:63]
	global_load_lds_dwordx4 v124, s[12:13] offset:-1024
	s_add_i32 m0, s19, 0xe500
	s_waitcnt lgkmcnt(5)
	v_mfma_f32_32x32x16_bf16 v[32:47], v[84:87], v[96:99], v[32:47]
	global_load_lds_dwordx4 v125, s[12:13] offset:-1024
	s_waitcnt lgkmcnt(4)
	v_mfma_f32_32x32x16_bf16 v[16:31], v[88:91], v[92:95], v[16:31]
	v_mfma_f32_32x32x16_bf16 v[0:15], v[88:91], v[96:99], v[0:15]
	s_setprio 0
	ds_read_b128 v[84:87], v234
	ds_read_b128 v[92:95], v238
	ds_read_b128 v[96:99], v238 offset:4096
	ds_read_b128 v[88:91], v234 offset:4096
	s_setprio 1
	s_add_i32 m0, s19, 0x10500
	s_waitcnt lgkmcnt(6)
	v_mfma_f32_32x32x16_bf16 v[48:63], v[102:105], v[110:113], v[48:63]
	global_load_lds_dwordx4 v124, s[14:15] offset:-1024
	s_add_i32 m0, s19, 0x12500
	s_waitcnt lgkmcnt(5)
	v_mfma_f32_32x32x16_bf16 v[32:47], v[102:105], v[114:117], v[32:47]
	global_load_lds_dwordx4 v125, s[14:15] offset:-1024
	s_waitcnt lgkmcnt(4)
	v_mfma_f32_32x32x16_bf16 v[16:31], v[106:109], v[110:113], v[16:31]
	v_mfma_f32_32x32x16_bf16 v[0:15], v[106:109], v[114:117], v[0:15]
	s_setprio 0
	ds_read_b128 v[102:105], v235
	ds_read_b128 v[110:113], v239
	ds_read_b128 v[114:117], v239 offset:4096
	ds_read_b128 v[106:109], v235 offset:4096
	s_setprio 1
	s_add_i32 m0, s19, 0x14500
	s_waitcnt lgkmcnt(6)
	v_mfma_f32_32x32x16_bf16 v[48:63], v[84:87], v[92:95], v[48:63]
	global_load_lds_dwordx4 v126, s[14:15] offset:-1024
	s_add_i32 m0, s19, 0x16500
	s_waitcnt lgkmcnt(5)
	v_mfma_f32_32x32x16_bf16 v[32:47], v[84:87], v[96:99], v[32:47]
	global_load_lds_dwordx4 v127, s[14:15] offset:-1024
	s_waitcnt lgkmcnt(4)
	v_mfma_f32_32x32x16_bf16 v[16:31], v[88:91], v[92:95], v[16:31]
	v_mfma_f32_32x32x16_bf16 v[0:15], v[88:91], v[96:99], v[0:15]
	s_setprio 0
	s_waitcnt lgkmcnt(0)
	s_waitcnt vmcnt(6)
	s_barrier
	ds_read_b128 v[84:87], v224
	ds_read_b128 v[92:95], v228
	ds_read_b128 v[96:99], v228 offset:4096
	ds_read_b128 v[88:91], v224 offset:4096
	s_setprio 1
	v_mfma_f32_32x32x16_bf16 v[48:63], v[102:105], v[110:113], v[48:63]
	v_mfma_f32_32x32x16_bf16 v[32:47], v[102:105], v[114:117], v[32:47]
	v_mfma_f32_32x32x16_bf16 v[16:31], v[106:109], v[110:113], v[16:31]
	v_mfma_f32_32x32x16_bf16 v[0:15], v[106:109], v[114:117], v[0:15]
	s_setprio 0
	ds_read_b128 v[102:105], v225
	ds_read_b128 v[110:113], v229
	ds_read_b128 v[114:117], v229 offset:4096
	ds_read_b128 v[106:109], v225 offset:4096
	s_setprio 1
	s_add_i32 m0, s19, 0x1bc80
	s_waitcnt lgkmcnt(6)
	v_mfma_f32_32x32x16_bf16 v[48:63], v[84:87], v[92:95], v[48:63]
	global_load_lds_dwordx4 v124, s[12:13] offset:-896
	s_add_i32 m0, s19, 0x1dc80
	s_waitcnt lgkmcnt(5)
	v_mfma_f32_32x32x16_bf16 v[32:47], v[84:87], v[96:99], v[32:47]
	global_load_lds_dwordx4 v125, s[12:13] offset:-896
	s_waitcnt lgkmcnt(4)
	v_mfma_f32_32x32x16_bf16 v[16:31], v[88:91], v[92:95], v[16:31]
	v_mfma_f32_32x32x16_bf16 v[0:15], v[88:91], v[96:99], v[0:15]
	s_setprio 0
	ds_read_b128 v[84:87], v226
	ds_read_b128 v[92:95], v230
	ds_read_b128 v[96:99], v230 offset:4096
	ds_read_b128 v[88:91], v226 offset:4096
	s_setprio 1
	s_add_i32 m0, s19, 0x1fc80
	s_waitcnt lgkmcnt(6)
	v_mfma_f32_32x32x16_bf16 v[48:63], v[102:105], v[110:113], v[48:63]
	global_load_lds_dwordx4 v124, s[14:15] offset:-896
	s_add_i32 m0, s19, 0x21c80
	s_waitcnt lgkmcnt(5)
	v_mfma_f32_32x32x16_bf16 v[32:47], v[102:105], v[114:117], v[32:47]
	global_load_lds_dwordx4 v125, s[14:15] offset:-896
	s_waitcnt lgkmcnt(4)
	v_mfma_f32_32x32x16_bf16 v[16:31], v[106:109], v[110:113], v[16:31]
	v_mfma_f32_32x32x16_bf16 v[0:15], v[106:109], v[114:117], v[0:15]
	s_setprio 0
	ds_read_b128 v[102:105], v227
	ds_read_b128 v[110:113], v231
	ds_read_b128 v[114:117], v231 offset:4096
	ds_read_b128 v[106:109], v227 offset:4096
	s_setprio 1
	s_add_i32 m0, s19, 0x23c80
	s_waitcnt lgkmcnt(6)
	v_mfma_f32_32x32x16_bf16 v[48:63], v[84:87], v[92:95], v[48:63]
	global_load_lds_dwordx4 v126, s[14:15] offset:-896
	s_add_i32 m0, s19, 0x25c80
	s_waitcnt lgkmcnt(5)
	v_mfma_f32_32x32x16_bf16 v[32:47], v[84:87], v[96:99], v[32:47]
	global_load_lds_dwordx4 v127, s[14:15] offset:-896
	s_waitcnt lgkmcnt(4)
	v_mfma_f32_32x32x16_bf16 v[16:31], v[88:91], v[92:95], v[16:31]
	v_mfma_f32_32x32x16_bf16 v[0:15], v[88:91], v[96:99], v[0:15]
	s_setprio 0
	s_waitcnt lgkmcnt(0)
	s_waitcnt vmcnt(6)
	s_barrier
	ds_read_b128 v[84:87], v224 offset:49152
	ds_read_b128 v[92:95], v228 offset:49152
	ds_read_b128 v[96:99], v228 offset:53248
	ds_read_b128 v[88:91], v224 offset:53248
	s_setprio 1
	v_mfma_f32_32x32x16_bf16 v[48:63], v[102:105], v[110:113], v[48:63]
	v_mfma_f32_32x32x16_bf16 v[32:47], v[102:105], v[114:117], v[32:47]
	v_mfma_f32_32x32x16_bf16 v[16:31], v[106:109], v[110:113], v[16:31]
	v_mfma_f32_32x32x16_bf16 v[0:15], v[106:109], v[114:117], v[0:15]
	s_setprio 0
	ds_read_b128 v[102:105], v225 offset:49152
	ds_read_b128 v[110:113], v229 offset:49152
	ds_read_b128 v[114:117], v229 offset:53248
	ds_read_b128 v[106:109], v225 offset:53248
	s_setprio 1
	s_add_i32 m0, s19, 0x400
	s_waitcnt lgkmcnt(6)
	v_mfma_f32_32x32x16_bf16 v[48:63], v[84:87], v[92:95], v[48:63]
	global_load_lds_dwordx4 v124, s[12:13] offset:-768
	s_add_i32 m0, s19, 0x2400
	s_waitcnt lgkmcnt(5)
	v_mfma_f32_32x32x16_bf16 v[32:47], v[84:87], v[96:99], v[32:47]
	global_load_lds_dwordx4 v125, s[12:13] offset:-768
	s_waitcnt lgkmcnt(4)
	v_mfma_f32_32x32x16_bf16 v[16:31], v[88:91], v[92:95], v[16:31]
	v_mfma_f32_32x32x16_bf16 v[0:15], v[88:91], v[96:99], v[0:15]
	s_setprio 0
	ds_read_b128 v[84:87], v226 offset:49152
	ds_read_b128 v[92:95], v230 offset:49152
	ds_read_b128 v[96:99], v230 offset:53248
	ds_read_b128 v[88:91], v226 offset:53248
	s_setprio 1
	s_add_i32 m0, s19, 0x4400
	s_waitcnt lgkmcnt(6)
	v_mfma_f32_32x32x16_bf16 v[48:63], v[102:105], v[110:113], v[48:63]
	global_load_lds_dwordx4 v124, s[14:15] offset:-768
	s_add_i32 m0, s19, 0x6400
	s_waitcnt lgkmcnt(5)
	v_mfma_f32_32x32x16_bf16 v[32:47], v[102:105], v[114:117], v[32:47]
	global_load_lds_dwordx4 v125, s[14:15] offset:-768
	s_waitcnt lgkmcnt(4)
	v_mfma_f32_32x32x16_bf16 v[16:31], v[106:109], v[110:113], v[16:31]
	v_mfma_f32_32x32x16_bf16 v[0:15], v[106:109], v[114:117], v[0:15]
	s_setprio 0
	ds_read_b128 v[102:105], v227 offset:49152
	ds_read_b128 v[110:113], v231 offset:49152
	ds_read_b128 v[114:117], v231 offset:53248
	ds_read_b128 v[106:109], v227 offset:53248
	s_setprio 1
	s_add_i32 m0, s19, 0x8400
	s_waitcnt lgkmcnt(6)
	v_mfma_f32_32x32x16_bf16 v[48:63], v[84:87], v[92:95], v[48:63]
	global_load_lds_dwordx4 v126, s[14:15] offset:-768
	s_add_i32 m0, s19, 0xa400
	s_waitcnt lgkmcnt(5)
	v_mfma_f32_32x32x16_bf16 v[32:47], v[84:87], v[96:99], v[32:47]
	global_load_lds_dwordx4 v127, s[14:15] offset:-768
	s_waitcnt lgkmcnt(4)
	v_mfma_f32_32x32x16_bf16 v[16:31], v[88:91], v[92:95], v[16:31]
	v_mfma_f32_32x32x16_bf16 v[0:15], v[88:91], v[96:99], v[0:15]
	s_setprio 0
	s_waitcnt lgkmcnt(0)
	s_waitcnt vmcnt(6)
	s_barrier
	ds_read_b128 v[84:87], v232
	ds_read_b128 v[92:95], v236
	ds_read_b128 v[96:99], v236 offset:4096
	ds_read_b128 v[88:91], v232 offset:4096
	s_setprio 1
	v_mfma_f32_32x32x16_bf16 v[48:63], v[102:105], v[110:113], v[48:63]
	v_mfma_f32_32x32x16_bf16 v[32:47], v[102:105], v[114:117], v[32:47]
	v_mfma_f32_32x32x16_bf16 v[16:31], v[106:109], v[110:113], v[16:31]
	v_mfma_f32_32x32x16_bf16 v[0:15], v[106:109], v[114:117], v[0:15]
	s_setprio 0
	ds_read_b128 v[102:105], v233
	ds_read_b128 v[110:113], v237
	ds_read_b128 v[114:117], v237 offset:4096
	ds_read_b128 v[106:109], v233 offset:4096
	s_setprio 1
	s_add_i32 m0, s19, 0xc380
	s_waitcnt lgkmcnt(6)
	v_mfma_f32_32x32x16_bf16 v[48:63], v[84:87], v[92:95], v[48:63]
	global_load_lds_dwordx4 v124, s[12:13] offset:-640
	s_add_i32 m0, s19, 0xe380
	s_waitcnt lgkmcnt(5)
	v_mfma_f32_32x32x16_bf16 v[32:47], v[84:87], v[96:99], v[32:47]
	global_load_lds_dwordx4 v125, s[12:13] offset:-640
	s_waitcnt lgkmcnt(4)
	v_mfma_f32_32x32x16_bf16 v[16:31], v[88:91], v[92:95], v[16:31]
	v_mfma_f32_32x32x16_bf16 v[0:15], v[88:91], v[96:99], v[0:15]
	s_setprio 0
	ds_read_b128 v[84:87], v234
	ds_read_b128 v[92:95], v238
	ds_read_b128 v[96:99], v238 offset:4096
	ds_read_b128 v[88:91], v234 offset:4096
	s_setprio 1
	s_add_i32 m0, s19, 0x10380
	s_waitcnt lgkmcnt(6)
	v_mfma_f32_32x32x16_bf16 v[48:63], v[102:105], v[110:113], v[48:63]
	global_load_lds_dwordx4 v124, s[14:15] offset:-640
	s_add_i32 m0, s19, 0x12380
	s_waitcnt lgkmcnt(5)
	v_mfma_f32_32x32x16_bf16 v[32:47], v[102:105], v[114:117], v[32:47]
	global_load_lds_dwordx4 v125, s[14:15] offset:-640
	s_waitcnt lgkmcnt(4)
	v_mfma_f32_32x32x16_bf16 v[16:31], v[106:109], v[110:113], v[16:31]
	v_mfma_f32_32x32x16_bf16 v[0:15], v[106:109], v[114:117], v[0:15]
	s_setprio 0
	ds_read_b128 v[102:105], v235
	ds_read_b128 v[110:113], v239
	ds_read_b128 v[114:117], v239 offset:4096
	ds_read_b128 v[106:109], v235 offset:4096
	s_setprio 1
	s_add_i32 m0, s19, 0x14380
	s_waitcnt lgkmcnt(6)
	v_mfma_f32_32x32x16_bf16 v[48:63], v[84:87], v[92:95], v[48:63]
	global_load_lds_dwordx4 v126, s[14:15] offset:-640
	s_add_i32 m0, s19, 0x16380
	s_waitcnt lgkmcnt(5)
	v_mfma_f32_32x32x16_bf16 v[32:47], v[84:87], v[96:99], v[32:47]
	global_load_lds_dwordx4 v127, s[14:15] offset:-640
	s_waitcnt lgkmcnt(4)
	v_mfma_f32_32x32x16_bf16 v[16:31], v[88:91], v[92:95], v[16:31]
	v_mfma_f32_32x32x16_bf16 v[0:15], v[88:91], v[96:99], v[0:15]
	s_setprio 0
	s_waitcnt lgkmcnt(0)
	s_waitcnt vmcnt(6)
	s_barrier
	ds_read_b128 v[84:87], v224
	ds_read_b128 v[92:95], v228
	ds_read_b128 v[96:99], v228 offset:4096
	ds_read_b128 v[88:91], v224 offset:4096
	s_setprio 1
	v_mfma_f32_32x32x16_bf16 v[48:63], v[102:105], v[110:113], v[48:63]
	v_mfma_f32_32x32x16_bf16 v[32:47], v[102:105], v[114:117], v[32:47]
	v_mfma_f32_32x32x16_bf16 v[16:31], v[106:109], v[110:113], v[16:31]
	v_mfma_f32_32x32x16_bf16 v[0:15], v[106:109], v[114:117], v[0:15]
	s_setprio 0
	ds_read_b128 v[102:105], v225
	ds_read_b128 v[110:113], v229
	ds_read_b128 v[114:117], v229 offset:4096
	ds_read_b128 v[106:109], v225 offset:4096
	s_setprio 1
	s_add_i32 m0, s19, 0x1bb00
	s_waitcnt lgkmcnt(6)
	v_mfma_f32_32x32x16_bf16 v[48:63], v[84:87], v[92:95], v[48:63]
	global_load_lds_dwordx4 v124, s[12:13] offset:-512
	s_add_i32 m0, s19, 0x1db00
	s_waitcnt lgkmcnt(5)
	v_mfma_f32_32x32x16_bf16 v[32:47], v[84:87], v[96:99], v[32:47]
	global_load_lds_dwordx4 v125, s[12:13] offset:-512
	s_waitcnt lgkmcnt(4)
	v_mfma_f32_32x32x16_bf16 v[16:31], v[88:91], v[92:95], v[16:31]
	v_mfma_f32_32x32x16_bf16 v[0:15], v[88:91], v[96:99], v[0:15]
	s_setprio 0
	ds_read_b128 v[84:87], v226
	ds_read_b128 v[92:95], v230
	ds_read_b128 v[96:99], v230 offset:4096
	ds_read_b128 v[88:91], v226 offset:4096
	s_setprio 1
	s_add_i32 m0, s19, 0x1fb00
	s_waitcnt lgkmcnt(6)
	v_mfma_f32_32x32x16_bf16 v[48:63], v[102:105], v[110:113], v[48:63]
	global_load_lds_dwordx4 v124, s[14:15] offset:-512
	s_add_i32 m0, s19, 0x21b00
	s_waitcnt lgkmcnt(5)
	v_mfma_f32_32x32x16_bf16 v[32:47], v[102:105], v[114:117], v[32:47]
	global_load_lds_dwordx4 v125, s[14:15] offset:-512
	s_waitcnt lgkmcnt(4)
	v_mfma_f32_32x32x16_bf16 v[16:31], v[106:109], v[110:113], v[16:31]
	v_mfma_f32_32x32x16_bf16 v[0:15], v[106:109], v[114:117], v[0:15]
	s_setprio 0
	ds_read_b128 v[102:105], v227
	ds_read_b128 v[110:113], v231
	ds_read_b128 v[114:117], v231 offset:4096
	ds_read_b128 v[106:109], v227 offset:4096
	s_setprio 1
	s_add_i32 m0, s19, 0x23b00
	s_waitcnt lgkmcnt(6)
	v_mfma_f32_32x32x16_bf16 v[48:63], v[84:87], v[92:95], v[48:63]
	global_load_lds_dwordx4 v126, s[14:15] offset:-512
	s_add_i32 m0, s19, 0x25b00
	s_waitcnt lgkmcnt(5)
	v_mfma_f32_32x32x16_bf16 v[32:47], v[84:87], v[96:99], v[32:47]
	global_load_lds_dwordx4 v127, s[14:15] offset:-512
	s_waitcnt lgkmcnt(4)
	v_mfma_f32_32x32x16_bf16 v[16:31], v[88:91], v[92:95], v[16:31]
	v_mfma_f32_32x32x16_bf16 v[0:15], v[88:91], v[96:99], v[0:15]
	s_setprio 0
	s_waitcnt lgkmcnt(0)
	s_waitcnt vmcnt(6)
	s_barrier
	ds_read_b128 v[84:87], v224 offset:49152
	ds_read_b128 v[92:95], v228 offset:49152
	ds_read_b128 v[96:99], v228 offset:53248
	ds_read_b128 v[88:91], v224 offset:53248
	s_setprio 1
	v_mfma_f32_32x32x16_bf16 v[48:63], v[102:105], v[110:113], v[48:63]
	v_mfma_f32_32x32x16_bf16 v[32:47], v[102:105], v[114:117], v[32:47]
	v_mfma_f32_32x32x16_bf16 v[16:31], v[106:109], v[110:113], v[16:31]
	v_mfma_f32_32x32x16_bf16 v[0:15], v[106:109], v[114:117], v[0:15]
	s_setprio 0
	ds_read_b128 v[102:105], v225 offset:49152
	ds_read_b128 v[110:113], v229 offset:49152
	ds_read_b128 v[114:117], v229 offset:53248
	ds_read_b128 v[106:109], v225 offset:53248
	s_setprio 1
	s_add_i32 m0, s19, 0x280
	s_waitcnt lgkmcnt(6)
	v_mfma_f32_32x32x16_bf16 v[48:63], v[84:87], v[92:95], v[48:63]
	global_load_lds_dwordx4 v124, s[12:13] offset:-384
	s_add_i32 m0, s19, 0x2280
	s_waitcnt lgkmcnt(5)
	v_mfma_f32_32x32x16_bf16 v[32:47], v[84:87], v[96:99], v[32:47]
	global_load_lds_dwordx4 v125, s[12:13] offset:-384
	s_waitcnt lgkmcnt(4)
	v_mfma_f32_32x32x16_bf16 v[16:31], v[88:91], v[92:95], v[16:31]
	v_mfma_f32_32x32x16_bf16 v[0:15], v[88:91], v[96:99], v[0:15]
	s_setprio 0
	ds_read_b128 v[84:87], v226 offset:49152
	ds_read_b128 v[92:95], v230 offset:49152
	ds_read_b128 v[96:99], v230 offset:53248
	ds_read_b128 v[88:91], v226 offset:53248
	s_setprio 1
	s_add_i32 m0, s19, 0x4280
	s_waitcnt lgkmcnt(6)
	v_mfma_f32_32x32x16_bf16 v[48:63], v[102:105], v[110:113], v[48:63]
	global_load_lds_dwordx4 v124, s[14:15] offset:-384
	s_add_i32 m0, s19, 0x6280
	s_waitcnt lgkmcnt(5)
	v_mfma_f32_32x32x16_bf16 v[32:47], v[102:105], v[114:117], v[32:47]
	global_load_lds_dwordx4 v125, s[14:15] offset:-384
	s_waitcnt lgkmcnt(4)
	v_mfma_f32_32x32x16_bf16 v[16:31], v[106:109], v[110:113], v[16:31]
	v_mfma_f32_32x32x16_bf16 v[0:15], v[106:109], v[114:117], v[0:15]
	s_setprio 0
	ds_read_b128 v[102:105], v227 offset:49152
	ds_read_b128 v[110:113], v231 offset:49152
	ds_read_b128 v[114:117], v231 offset:53248
	ds_read_b128 v[106:109], v227 offset:53248
	s_setprio 1
	s_add_i32 m0, s19, 0x8280
	s_waitcnt lgkmcnt(6)
	v_mfma_f32_32x32x16_bf16 v[48:63], v[84:87], v[92:95], v[48:63]
	global_load_lds_dwordx4 v126, s[14:15] offset:-384
	s_add_i32 m0, s19, 0xa280
	s_waitcnt lgkmcnt(5)
	v_mfma_f32_32x32x16_bf16 v[32:47], v[84:87], v[96:99], v[32:47]
	global_load_lds_dwordx4 v127, s[14:15] offset:-384
	s_waitcnt lgkmcnt(4)
	v_mfma_f32_32x32x16_bf16 v[16:31], v[88:91], v[92:95], v[16:31]
	v_mfma_f32_32x32x16_bf16 v[0:15], v[88:91], v[96:99], v[0:15]
	s_setprio 0
	s_waitcnt lgkmcnt(0)
	s_waitcnt vmcnt(6)
	s_barrier
	ds_read_b128 v[84:87], v232
	ds_read_b128 v[92:95], v236
	ds_read_b128 v[96:99], v236 offset:4096
	ds_read_b128 v[88:91], v232 offset:4096
	s_setprio 1
	v_mfma_f32_32x32x16_bf16 v[48:63], v[102:105], v[110:113], v[48:63]
	v_mfma_f32_32x32x16_bf16 v[32:47], v[102:105], v[114:117], v[32:47]
	v_mfma_f32_32x32x16_bf16 v[16:31], v[106:109], v[110:113], v[16:31]
	v_mfma_f32_32x32x16_bf16 v[0:15], v[106:109], v[114:117], v[0:15]
	s_setprio 0
	ds_read_b128 v[102:105], v233
	ds_read_b128 v[110:113], v237
	ds_read_b128 v[114:117], v237 offset:4096
	ds_read_b128 v[106:109], v233 offset:4096
	s_setprio 1
	s_add_i32 m0, s19, 0xc200
	s_waitcnt lgkmcnt(6)
	v_mfma_f32_32x32x16_bf16 v[48:63], v[84:87], v[92:95], v[48:63]
	global_load_lds_dwordx4 v124, s[12:13] offset:-256
	s_add_i32 m0, s19, 0xe200
	s_waitcnt lgkmcnt(5)
	v_mfma_f32_32x32x16_bf16 v[32:47], v[84:87], v[96:99], v[32:47]
	global_load_lds_dwordx4 v125, s[12:13] offset:-256
	s_waitcnt lgkmcnt(4)
	v_mfma_f32_32x32x16_bf16 v[16:31], v[88:91], v[92:95], v[16:31]
	v_mfma_f32_32x32x16_bf16 v[0:15], v[88:91], v[96:99], v[0:15]
	s_setprio 0
	ds_read_b128 v[84:87], v234
	ds_read_b128 v[92:95], v238
	ds_read_b128 v[96:99], v238 offset:4096
	ds_read_b128 v[88:91], v234 offset:4096
	s_setprio 1
	s_add_i32 m0, s19, 0x10200
	s_waitcnt lgkmcnt(6)
	v_mfma_f32_32x32x16_bf16 v[48:63], v[102:105], v[110:113], v[48:63]
	global_load_lds_dwordx4 v124, s[14:15] offset:-256
	s_add_i32 m0, s19, 0x12200
	s_waitcnt lgkmcnt(5)
	v_mfma_f32_32x32x16_bf16 v[32:47], v[102:105], v[114:117], v[32:47]
	global_load_lds_dwordx4 v125, s[14:15] offset:-256
	s_waitcnt lgkmcnt(4)
	v_mfma_f32_32x32x16_bf16 v[16:31], v[106:109], v[110:113], v[16:31]
	v_mfma_f32_32x32x16_bf16 v[0:15], v[106:109], v[114:117], v[0:15]
	s_setprio 0
	ds_read_b128 v[102:105], v235
	ds_read_b128 v[110:113], v239
	ds_read_b128 v[114:117], v239 offset:4096
	ds_read_b128 v[106:109], v235 offset:4096
	s_setprio 1
	s_add_i32 m0, s19, 0x14200
	s_waitcnt lgkmcnt(6)
	v_mfma_f32_32x32x16_bf16 v[48:63], v[84:87], v[92:95], v[48:63]
	global_load_lds_dwordx4 v126, s[14:15] offset:-256
	s_add_i32 m0, s19, 0x16200
	s_waitcnt lgkmcnt(5)
	v_mfma_f32_32x32x16_bf16 v[32:47], v[84:87], v[96:99], v[32:47]
	global_load_lds_dwordx4 v127, s[14:15] offset:-256
	s_waitcnt lgkmcnt(4)
	v_mfma_f32_32x32x16_bf16 v[16:31], v[88:91], v[92:95], v[16:31]
	v_mfma_f32_32x32x16_bf16 v[0:15], v[88:91], v[96:99], v[0:15]
	s_setprio 0
	s_waitcnt lgkmcnt(0)
	s_waitcnt vmcnt(6)
	s_barrier
	ds_read_b128 v[84:87], v224
	ds_read_b128 v[92:95], v228
	ds_read_b128 v[96:99], v228 offset:4096
	ds_read_b128 v[88:91], v224 offset:4096
	s_setprio 1
	v_mfma_f32_32x32x16_bf16 v[48:63], v[102:105], v[110:113], v[48:63]
	v_mfma_f32_32x32x16_bf16 v[32:47], v[102:105], v[114:117], v[32:47]
	v_mfma_f32_32x32x16_bf16 v[16:31], v[106:109], v[110:113], v[16:31]
	v_mfma_f32_32x32x16_bf16 v[0:15], v[106:109], v[114:117], v[0:15]
	s_setprio 0
	ds_read_b128 v[102:105], v225
	ds_read_b128 v[110:113], v229
	ds_read_b128 v[114:117], v229 offset:4096
	ds_read_b128 v[106:109], v225 offset:4096
	s_setprio 1
	s_add_i32 m0, s19, 0x1b980
	s_waitcnt lgkmcnt(6)
	v_mfma_f32_32x32x16_bf16 v[48:63], v[84:87], v[92:95], v[48:63]
	global_load_lds_dwordx4 v124, s[12:13] offset:-128
	s_add_i32 m0, s19, 0x1d980
	s_waitcnt lgkmcnt(5)
	v_mfma_f32_32x32x16_bf16 v[32:47], v[84:87], v[96:99], v[32:47]
	global_load_lds_dwordx4 v125, s[12:13] offset:-128
	s_waitcnt lgkmcnt(4)
	v_mfma_f32_32x32x16_bf16 v[16:31], v[88:91], v[92:95], v[16:31]
	v_mfma_f32_32x32x16_bf16 v[0:15], v[88:91], v[96:99], v[0:15]
	s_setprio 0
	ds_read_b128 v[84:87], v226
	ds_read_b128 v[92:95], v230
	ds_read_b128 v[96:99], v230 offset:4096
	ds_read_b128 v[88:91], v226 offset:4096
	s_setprio 1
	s_add_i32 m0, s19, 0x1f980
	s_waitcnt lgkmcnt(6)
	v_mfma_f32_32x32x16_bf16 v[48:63], v[102:105], v[110:113], v[48:63]
	global_load_lds_dwordx4 v124, s[14:15] offset:-128
	s_add_i32 m0, s19, 0x21980
	s_waitcnt lgkmcnt(5)
	v_mfma_f32_32x32x16_bf16 v[32:47], v[102:105], v[114:117], v[32:47]
	global_load_lds_dwordx4 v125, s[14:15] offset:-128
	s_waitcnt lgkmcnt(4)
	v_mfma_f32_32x32x16_bf16 v[16:31], v[106:109], v[110:113], v[16:31]
	v_mfma_f32_32x32x16_bf16 v[0:15], v[106:109], v[114:117], v[0:15]
	s_setprio 0
	ds_read_b128 v[102:105], v227
	ds_read_b128 v[110:113], v231
	ds_read_b128 v[114:117], v231 offset:4096
	ds_read_b128 v[106:109], v227 offset:4096
	s_setprio 1
	s_add_i32 m0, s19, 0x23980
	s_waitcnt lgkmcnt(6)
	v_mfma_f32_32x32x16_bf16 v[48:63], v[84:87], v[92:95], v[48:63]
	global_load_lds_dwordx4 v126, s[14:15] offset:-128
	s_add_i32 m0, s19, 0x25980
	s_waitcnt lgkmcnt(5)
	v_mfma_f32_32x32x16_bf16 v[32:47], v[84:87], v[96:99], v[32:47]
	global_load_lds_dwordx4 v127, s[14:15] offset:-128
	s_waitcnt lgkmcnt(4)
	v_mfma_f32_32x32x16_bf16 v[16:31], v[88:91], v[92:95], v[16:31]
	v_mfma_f32_32x32x16_bf16 v[0:15], v[88:91], v[96:99], v[0:15]
	s_setprio 0
	s_waitcnt lgkmcnt(0)
	s_waitcnt vmcnt(6)
	s_barrier
	ds_read_b128 v[84:87], v224 offset:49152
	ds_read_b128 v[92:95], v228 offset:49152
	ds_read_b128 v[96:99], v228 offset:53248
	ds_read_b128 v[88:91], v224 offset:53248
	s_setprio 1
	v_mfma_f32_32x32x16_bf16 v[48:63], v[102:105], v[110:113], v[48:63]
	v_mfma_f32_32x32x16_bf16 v[32:47], v[102:105], v[114:117], v[32:47]
	v_mfma_f32_32x32x16_bf16 v[16:31], v[106:109], v[110:113], v[16:31]
	v_mfma_f32_32x32x16_bf16 v[0:15], v[106:109], v[114:117], v[0:15]
	s_setprio 0
	ds_read_b128 v[102:105], v225 offset:49152
	ds_read_b128 v[110:113], v229 offset:49152
	ds_read_b128 v[114:117], v229 offset:53248
	ds_read_b128 v[106:109], v225 offset:53248
	s_setprio 1
	s_add_i32 m0, s19, 0x100
	s_waitcnt lgkmcnt(6)
	v_mfma_f32_32x32x16_bf16 v[48:63], v[84:87], v[92:95], v[48:63]
	global_load_lds_dwordx4 v124, s[12:13]
	s_add_i32 m0, s19, 0x2100
	s_waitcnt lgkmcnt(5)
	v_mfma_f32_32x32x16_bf16 v[32:47], v[84:87], v[96:99], v[32:47]
	global_load_lds_dwordx4 v125, s[12:13]
	s_waitcnt lgkmcnt(4)
	v_mfma_f32_32x32x16_bf16 v[16:31], v[88:91], v[92:95], v[16:31]
	v_mfma_f32_32x32x16_bf16 v[0:15], v[88:91], v[96:99], v[0:15]
	s_setprio 0
	ds_read_b128 v[84:87], v226 offset:49152
	ds_read_b128 v[92:95], v230 offset:49152
	ds_read_b128 v[96:99], v230 offset:53248
	ds_read_b128 v[88:91], v226 offset:53248
	s_setprio 1
	s_add_i32 m0, s19, 0x4100
	s_waitcnt lgkmcnt(6)
	v_mfma_f32_32x32x16_bf16 v[48:63], v[102:105], v[110:113], v[48:63]
	global_load_lds_dwordx4 v124, s[14:15]
	s_add_i32 m0, s19, 0x6100
	s_waitcnt lgkmcnt(5)
	v_mfma_f32_32x32x16_bf16 v[32:47], v[102:105], v[114:117], v[32:47]
	global_load_lds_dwordx4 v125, s[14:15]
	s_waitcnt lgkmcnt(4)
	v_mfma_f32_32x32x16_bf16 v[16:31], v[106:109], v[110:113], v[16:31]
	v_mfma_f32_32x32x16_bf16 v[0:15], v[106:109], v[114:117], v[0:15]
	s_setprio 0
	ds_read_b128 v[102:105], v227 offset:49152
	ds_read_b128 v[110:113], v231 offset:49152
	ds_read_b128 v[114:117], v231 offset:53248
	ds_read_b128 v[106:109], v227 offset:53248
	s_setprio 1
	s_add_i32 m0, s19, 0x8100
	s_waitcnt lgkmcnt(6)
	v_mfma_f32_32x32x16_bf16 v[48:63], v[84:87], v[92:95], v[48:63]
	global_load_lds_dwordx4 v126, s[14:15]
	s_add_i32 m0, s19, 0xa100
	s_waitcnt lgkmcnt(5)
	v_mfma_f32_32x32x16_bf16 v[32:47], v[84:87], v[96:99], v[32:47]
	global_load_lds_dwordx4 v127, s[14:15]
	s_waitcnt lgkmcnt(4)
	v_mfma_f32_32x32x16_bf16 v[16:31], v[88:91], v[92:95], v[16:31]
	v_mfma_f32_32x32x16_bf16 v[0:15], v[88:91], v[96:99], v[0:15]
	s_setprio 0
	s_waitcnt lgkmcnt(0)
	s_waitcnt vmcnt(6)
	s_barrier
	ds_read_b128 v[84:87], v232
	ds_read_b128 v[92:95], v236
	ds_read_b128 v[96:99], v236 offset:4096
	ds_read_b128 v[88:91], v232 offset:4096
	s_setprio 1
	v_mfma_f32_32x32x16_bf16 v[48:63], v[102:105], v[110:113], v[48:63]
	v_mfma_f32_32x32x16_bf16 v[32:47], v[102:105], v[114:117], v[32:47]
	v_mfma_f32_32x32x16_bf16 v[16:31], v[106:109], v[110:113], v[16:31]
	v_mfma_f32_32x32x16_bf16 v[0:15], v[106:109], v[114:117], v[0:15]
	s_setprio 0
	ds_read_b128 v[102:105], v233
	ds_read_b128 v[110:113], v237
	ds_read_b128 v[114:117], v237 offset:4096
	ds_read_b128 v[106:109], v233 offset:4096
	s_setprio 1
	s_waitcnt lgkmcnt(6)
	v_mfma_f32_32x32x16_bf16 v[48:63], v[84:87], v[92:95], v[48:63]
	s_waitcnt lgkmcnt(5)
	v_mfma_f32_32x32x16_bf16 v[32:47], v[84:87], v[96:99], v[32:47]
	s_waitcnt lgkmcnt(4)
	v_mfma_f32_32x32x16_bf16 v[16:31], v[88:91], v[92:95], v[16:31]
	v_mfma_f32_32x32x16_bf16 v[0:15], v[88:91], v[96:99], v[0:15]
	s_setprio 0
	ds_read_b128 v[84:87], v234
	ds_read_b128 v[92:95], v238
	ds_read_b128 v[96:99], v238 offset:4096
	ds_read_b128 v[88:91], v234 offset:4096
	s_setprio 1
	s_waitcnt lgkmcnt(6)
	v_mfma_f32_32x32x16_bf16 v[48:63], v[102:105], v[110:113], v[48:63]
	s_waitcnt lgkmcnt(5)
	v_mfma_f32_32x32x16_bf16 v[32:47], v[102:105], v[114:117], v[32:47]
	s_waitcnt lgkmcnt(4)
	v_mfma_f32_32x32x16_bf16 v[16:31], v[106:109], v[110:113], v[16:31]
	v_mfma_f32_32x32x16_bf16 v[0:15], v[106:109], v[114:117], v[0:15]
	s_setprio 0
	ds_read_b128 v[102:105], v235
	ds_read_b128 v[110:113], v239
	ds_read_b128 v[114:117], v239 offset:4096
	ds_read_b128 v[106:109], v235 offset:4096
	s_setprio 1
	s_waitcnt lgkmcnt(6)
	v_mfma_f32_32x32x16_bf16 v[48:63], v[84:87], v[92:95], v[48:63]
	s_waitcnt lgkmcnt(5)
	v_mfma_f32_32x32x16_bf16 v[32:47], v[84:87], v[96:99], v[32:47]
	s_waitcnt lgkmcnt(4)
	v_mfma_f32_32x32x16_bf16 v[16:31], v[88:91], v[92:95], v[16:31]
	v_mfma_f32_32x32x16_bf16 v[0:15], v[88:91], v[96:99], v[0:15]
	s_setprio 0
	s_waitcnt lgkmcnt(0)
	s_waitcnt vmcnt(0)
	s_barrier
	ds_read_b128 v[84:87], v224
	ds_read_b128 v[92:95], v228
	ds_read_b128 v[96:99], v228 offset:4096
	ds_read_b128 v[88:91], v224 offset:4096
	s_setprio 1
	v_mfma_f32_32x32x16_bf16 v[48:63], v[102:105], v[110:113], v[48:63]
	v_mfma_f32_32x32x16_bf16 v[32:47], v[102:105], v[114:117], v[32:47]
	v_mfma_f32_32x32x16_bf16 v[16:31], v[106:109], v[110:113], v[16:31]
	v_mfma_f32_32x32x16_bf16 v[0:15], v[106:109], v[114:117], v[0:15]
	s_setprio 0
	ds_read_b128 v[102:105], v225
	ds_read_b128 v[110:113], v229
	ds_read_b128 v[114:117], v229 offset:4096
	ds_read_b128 v[106:109], v225 offset:4096
	s_setprio 1
	s_waitcnt lgkmcnt(6)
	v_mfma_f32_32x32x16_bf16 v[48:63], v[84:87], v[92:95], v[48:63]
	s_waitcnt lgkmcnt(5)
	v_mfma_f32_32x32x16_bf16 v[32:47], v[84:87], v[96:99], v[32:47]
	s_waitcnt lgkmcnt(4)
	v_mfma_f32_32x32x16_bf16 v[16:31], v[88:91], v[92:95], v[16:31]
	v_mfma_f32_32x32x16_bf16 v[0:15], v[88:91], v[96:99], v[0:15]
	s_setprio 0
	ds_read_b128 v[84:87], v226
	ds_read_b128 v[92:95], v230
	ds_read_b128 v[96:99], v230 offset:4096
	ds_read_b128 v[88:91], v226 offset:4096
	s_setprio 1
	s_waitcnt lgkmcnt(6)
	v_mfma_f32_32x32x16_bf16 v[48:63], v[102:105], v[110:113], v[48:63]
	s_waitcnt lgkmcnt(5)
	v_mfma_f32_32x32x16_bf16 v[32:47], v[102:105], v[114:117], v[32:47]
	s_waitcnt lgkmcnt(4)
	v_mfma_f32_32x32x16_bf16 v[16:31], v[106:109], v[110:113], v[16:31]
	v_mfma_f32_32x32x16_bf16 v[0:15], v[106:109], v[114:117], v[0:15]
	s_setprio 0
	ds_read_b128 v[102:105], v227
	ds_read_b128 v[110:113], v231
	ds_read_b128 v[114:117], v231 offset:4096
	ds_read_b128 v[106:109], v227 offset:4096
	s_setprio 1
	s_waitcnt lgkmcnt(6)
	v_mfma_f32_32x32x16_bf16 v[48:63], v[84:87], v[92:95], v[48:63]
	s_waitcnt lgkmcnt(5)
	v_mfma_f32_32x32x16_bf16 v[32:47], v[84:87], v[96:99], v[32:47]
	s_waitcnt lgkmcnt(4)
	v_mfma_f32_32x32x16_bf16 v[16:31], v[88:91], v[92:95], v[16:31]
	v_mfma_f32_32x32x16_bf16 v[0:15], v[88:91], v[96:99], v[0:15]
	s_setprio 0
	s_waitcnt lgkmcnt(0)
	s_waitcnt vmcnt(0)
	s_barrier
